# GEMM compute segments: redundant s_setprio 0 / s_setprio 1 flip between the two 16-MFMA blocks removed (24 sites; priority stays 1 across the 32 MFMAs)
# speedup vs baseline: 1.0033x; 1.0033x over previous
; #define PG8_STAGE(bufoff, gbase, voff) do { _Pragma("unroll") for (int _i = 0; _i < 2; ++_i) \
;         __builtin_amdgcn_global_load_lds((const unsigned*)((const char*)(gbase) + (voff)[_i]), (PG8_LAS unsigned*)(lds + (bufoff) + ldsw + _i * 8192), 16, 0, 0); } while (0)
; #define PG8_LDA(dst, b, h) do { _Pragma("unroll") for (int m = 0; m < 4; ++m) _Pragma("unroll") for (int k = 0; k < 2; ++k) dst[m][k] = *(const PG8_LAS bf16x8*)(lds + PG8_SA(b, h) + aoff + m * 2048 + k * 1024); } while (0)
; #define PG8_LDB(dst, b, h) do { _Pragma("unroll") for (int n = 0; n < 2; ++n) _Pragma("unroll") for (int k = 0; k < 2; ++k) dst[n][k] = *(const PG8_LAS bf16x8*)(lds + PG8_SB(b, h) + boff + n * 2048 + k * 1024); } while (0)
; #define PG8_MMA(ai, bj, At, Bt) do { __builtin_amdgcn_s_setprio(1); _Pragma("unroll") for (int m = 0; m < 4; ++m) _Pragma("unroll") for (int n = 0; n < 2; ++n) _Pragma("unroll") for (int k = 0; k < 2; ++k) \
;         acc[ai][bj][m][n] = __builtin_amdgcn_mfma_f32_16x16x32_bf16(Bt[n][k], At[m][k], acc[ai][bj][m][n], 0, 0, 0); __builtin_amdgcn_s_setprio(0); } while (0)
; #define PG8_WAIT_V(n) asm volatile("s_waitcnt vmcnt(" #n ")" ::: "memory")
; #define PG8_WAIT_L(n) asm volatile("s_waitcnt lgkmcnt(" #n ")" ::: "memory")
; #define PG8_BAR __builtin_amdgcn_s_barrier()
; #define PG8_SCHED __builtin_amdgcn_sched_barrier(0)
; template <class Epi, class Sched, bool ALIGN_EPI = false, bool SP2 = false>
; __device__ __forceinline__ void gemm_phase(PG8_LAS unsigned char* lds, const Gemm g, const Sched& S, const Epi& E) {
;     ...
;         for (int t = 0; t < nt; t += 2) {
;             const bool last = (t == nt - 2);
;             const char* a1 = cA + (size_t)(t + 1) * kstep;
;             const char* a2 = last ? nA : cA + (size_t)(t + 2) * kstep; const char* b2 = last ? nB : cB + (size_t)(t + 2) * kstep;
;             const char* a3 = a2 + kstep; const char* b3 = b2 + kstep;
;             if (last && has_next) S.a_ready(nxt);
;             if constexpr (SP2) {
;             PG8_LDB(B0, 0, 0); PG8_LDB(B1, 0, 1); PG8_SCHED; PG8_LDA(At, 0, 0); PG8_STAGE(PG8_SA(1, 1), a1 + hstep, voffA);
;             PG8_WAIT_V(8); PG8_WAIT_L(0); PG8_BAR; PG8_MMA(0, 0, At, B0); PG8_MMA(0, 1, At, B1); PG8_BAR; PG8_SCHED;
;             PG8_LDA(At, 0, 1); PG8_STAGE(PG8_SB(0, 0), b2, voffB); PG8_STAGE(PG8_SB(0, 1), b2 + hstep, voffB); PG8_STAGE(PG8_SA(0, 0), a2, voffA);
.LBB0_71:
	s_add_u32 s18, s16, 0xfffc0080
	s_addc_u32 s19, s17, -1
	s_cmp_eq_u32 s38, 12
	s_cselect_b32 s21, s9, s19
	s_cselect_b32 s20, s34, s18
	s_cselect_b32 s19, s7, s37
	s_cselect_b32 s18, s35, s36
	s_add_i32 s39, 0, 0x10000
	s_add_i32 s44, 0, 0x14000
	v_add_u32_e32 v154, s39, v140
	v_add_u32_e32 v170, s44, v140
	ds_read_b128 v[142:145], v154
	ds_read_b128 v[146:149], v154 offset:1024
	ds_read_b128 v[150:153], v154 offset:2048
	ds_read_b128 v[154:157], v154 offset:3072
	ds_read_b128 v[158:161], v170
	ds_read_b128 v[162:165], v170 offset:1024
	ds_read_b128 v[166:169], v170 offset:2048
	ds_read_b128 v[170:173], v170 offset:3072
	v_lshl_add_u64 v[210:211], s[16:17], 0, v[136:137]
	s_add_i32 m0, s25, 0xc000
	ds_read_b128 v[174:177], v141
	ds_read_b128 v[178:181], v141 offset:1024
	ds_read_b128 v[182:185], v141 offset:2048
	ds_read_b128 v[186:189], v141 offset:3072
	ds_read_b128 v[190:193], v141 offset:4096
	ds_read_b128 v[194:197], v141 offset:5120
	ds_read_b128 v[198:201], v141 offset:6144
	ds_read_b128 v[206:209], v141 offset:7168
	global_load_lds_dwordx4 v[210:211], off
	v_lshl_add_u64 v[210:211], s[16:17], 0, v[138:139]
	s_add_i32 m0, s25, 0xe000
	s_nop 0
	global_load_lds_dwordx4 v[210:211], off
	s_waitcnt vmcnt(8)
	s_waitcnt lgkmcnt(0)
	s_barrier
	s_setprio 1
	s_waitcnt lgkmcnt(0)
	v_mfma_f32_16x16x32_bf16 v[126:129], v[142:145], v[174:177], v[126:129]
	v_mfma_f32_16x16x32_bf16 v[122:125], v[150:153], v[174:177], v[122:125]
	v_mfma_f32_16x16x32_bf16 v[110:113], v[142:145], v[182:185], v[110:113]
	v_mfma_f32_16x16x32_bf16 v[106:109], v[150:153], v[182:185], v[106:109]
	v_mfma_f32_16x16x32_bf16 v[94:97], v[142:145], v[190:193], v[94:97]
	v_mfma_f32_16x16x32_bf16 v[90:93], v[150:153], v[190:193], v[90:93]
	v_mfma_f32_16x16x32_bf16 v[78:81], v[142:145], v[198:201], v[78:81]
	v_mfma_f32_16x16x32_bf16 v[74:77], v[150:153], v[198:201], v[74:77]
	v_mfma_f32_16x16x32_bf16 v[126:129], v[146:149], v[178:181], v[126:129]
	v_mfma_f32_16x16x32_bf16 v[122:125], v[154:157], v[178:181], v[122:125]
	v_mfma_f32_16x16x32_bf16 v[110:113], v[146:149], v[186:189], v[110:113]
	v_mfma_f32_16x16x32_bf16 v[106:109], v[154:157], v[186:189], v[106:109]
	v_mfma_f32_16x16x32_bf16 v[94:97], v[146:149], v[194:197], v[94:97]
	v_mfma_f32_16x16x32_bf16 v[90:93], v[154:157], v[194:197], v[90:93]
	v_mfma_f32_16x16x32_bf16 v[78:81], v[146:149], v[206:209], v[78:81]
	v_mfma_f32_16x16x32_bf16 v[74:77], v[154:157], v[206:209], v[74:77]
	v_mfma_f32_16x16x32_bf16 v[118:121], v[158:161], v[174:177], v[118:121]
	v_mfma_f32_16x16x32_bf16 v[114:117], v[166:169], v[174:177], v[114:117]
	v_mfma_f32_16x16x32_bf16 v[102:105], v[158:161], v[182:185], v[102:105]
	v_mfma_f32_16x16x32_bf16 v[98:101], v[166:169], v[182:185], v[98:101]
	v_mfma_f32_16x16x32_bf16 v[86:89], v[158:161], v[190:193], v[86:89]
	v_mfma_f32_16x16x32_bf16 v[82:85], v[166:169], v[190:193], v[82:85]
	v_mfma_f32_16x16x32_bf16 v[70:73], v[158:161], v[198:201], v[70:73]
	v_mfma_f32_16x16x32_bf16 v[66:69], v[166:169], v[198:201], v[66:69]
	v_mfma_f32_16x16x32_bf16 v[118:121], v[162:165], v[178:181], v[118:121]
	v_mfma_f32_16x16x32_bf16 v[114:117], v[170:173], v[178:181], v[114:117]
	v_mfma_f32_16x16x32_bf16 v[102:105], v[162:165], v[186:189], v[102:105]
	v_mfma_f32_16x16x32_bf16 v[98:101], v[170:173], v[186:189], v[98:101]
	v_mfma_f32_16x16x32_bf16 v[86:89], v[162:165], v[194:197], v[86:89]
	v_mfma_f32_16x16x32_bf16 v[82:85], v[170:173], v[194:197], v[82:85]
	v_mfma_f32_16x16x32_bf16 v[70:73], v[162:165], v[206:209], v[70:73]
	v_mfma_f32_16x16x32_bf16 v[66:69], v[170:173], v[206:209], v[66:69]
	s_setprio 0
	s_barrier
	s_add_i32 s39, s39, s23
	v_lshl_add_u64 v[210:211], s[18:19], 0, v[0:1]
	s_mov_b32 m0, s39
	ds_read_b128 v[174:177], v141 offset:16384
	ds_read_b128 v[178:181], v141 offset:17408
	ds_read_b128 v[182:185], v141 offset:18432
	ds_read_b128 v[186:189], v141 offset:19456
	ds_read_b128 v[190:193], v141 offset:20480
	ds_read_b128 v[194:197], v141 offset:21504
	ds_read_b128 v[198:201], v141 offset:22528
	ds_read_b128 v[206:209], v141 offset:23552
	global_load_lds_dwordx4 v[210:211], off
	s_add_i32 m0, s39, 0x2000
	s_add_u32 s40, s18, 0x40000
	v_lshl_add_u64 v[212:213], s[18:19], 0, v[130:131]
	s_addc_u32 s41, s19, 0
	s_add_i32 s39, s44, s23
	global_load_lds_dwordx4 v[212:213], off
	v_lshl_add_u64 v[214:215], s[40:41], 0, v[0:1]
	s_mov_b32 m0, s39
	v_lshl_add_u64 v[216:217], s[20:21], 0, v[132:133]
	global_load_lds_dwordx4 v[214:215], off
	v_lshl_add_u64 v[214:215], s[40:41], 0, v[130:131]
	s_add_i32 m0, s39, 0x2000
	s_nop 0
	global_load_lds_dwordx4 v[214:215], off
	v_lshl_add_u64 v[214:215], s[20:21], 0, v[134:135]
	s_mov_b32 m0, s25
	s_nop 0
	global_load_lds_dwordx4 v[214:215], off
	s_mov_b32 m0, s26
	s_nop 0
	global_load_lds_dwordx4 v[216:217], off
	s_waitcnt vmcnt(8)
	s_waitcnt lgkmcnt(0)
	s_barrier
; #define PG8_STAGE(bufoff, gbase, voff) do { _Pragma("unroll") for (int _i = 0; _i < 2; ++_i) \
;         __builtin_amdgcn_global_load_lds((const unsigned*)((const char*)(gbase) + (voff)[_i]), (PG8_LAS unsigned*)(lds + (bufoff) + ldsw + _i * 8192), 16, 0, 0); } while (0)
; #define PG8_LDA(dst, b, h) do { _Pragma("unroll") for (int m = 0; m < 4; ++m) _Pragma("unroll") for (int k = 0; k < 2; ++k) dst[m][k] = *(const PG8_LAS bf16x8*)(lds + PG8_SA(b, h) + aoff + m * 2048 + k * 1024); } while (0)
; #define PG8_LDB(dst, b, h) do { _Pragma("unroll") for (int n = 0; n < 2; ++n) _Pragma("unroll") for (int k = 0; k < 2; ++k) dst[n][k] = *(const PG8_LAS bf16x8*)(lds + PG8_SB(b, h) + boff + n * 2048 + k * 1024); } while (0)
; #define PG8_MMA(ai, bj, At, Bt) do { __builtin_amdgcn_s_setprio(1); _Pragma("unroll") for (int m = 0; m < 4; ++m) _Pragma("unroll") for (int n = 0; n < 2; ++n) _Pragma("unroll") for (int k = 0; k < 2; ++k) \
;         acc[ai][bj][m][n] = __builtin_amdgcn_mfma_f32_16x16x32_bf16(Bt[n][k], At[m][k], acc[ai][bj][m][n], 0, 0, 0); __builtin_amdgcn_s_setprio(0); } while (0)
; #define PG8_WAIT_V(n) asm volatile("s_waitcnt vmcnt(" #n ")" ::: "memory")
; #define PG8_WAIT_L(n) asm volatile("s_waitcnt lgkmcnt(" #n ")" ::: "memory")
; #define PG8_BAR __builtin_amdgcn_s_barrier()
; #define PG8_SCHED __builtin_amdgcn_sched_barrier(0)
; template <class Epi, class Sched, bool ALIGN_EPI = false, bool SP2 = false>
; __device__ __forceinline__ void gemm_phase(PG8_LAS unsigned char* lds, const Gemm g, const Sched& S, const Epi& E) {
;     ...
;             PG8_WAIT_V(8); PG8_WAIT_L(0); PG8_BAR; PG8_MMA(1, 0, At, B0); PG8_MMA(1, 1, At, B1); PG8_BAR; PG8_SCHED;
;             PG8_LDB(B0, 1, 0); PG8_LDB(B1, 1, 1); PG8_SCHED; PG8_LDA(At, 1, 0); PG8_STAGE(PG8_SA(0, 1), a2 + hstep, voffA);
;             PG8_WAIT_V(8); PG8_WAIT_L(0); PG8_BAR; PG8_MMA(0, 0, At, B0); PG8_MMA(0, 1, At, B1); PG8_BAR; PG8_SCHED;
	s_setprio 1
	s_waitcnt lgkmcnt(0)
	v_mfma_f32_16x16x32_bf16 v[62:65], v[142:145], v[174:177], v[62:65]
	v_mfma_f32_16x16x32_bf16 v[58:61], v[150:153], v[174:177], v[58:61]
	v_mfma_f32_16x16x32_bf16 v[46:49], v[142:145], v[182:185], v[46:49]
	v_mfma_f32_16x16x32_bf16 v[42:45], v[150:153], v[182:185], v[42:45]
	v_mfma_f32_16x16x32_bf16 v[30:33], v[142:145], v[190:193], v[30:33]
	v_mfma_f32_16x16x32_bf16 v[26:29], v[150:153], v[190:193], v[26:29]
	v_mfma_f32_16x16x32_bf16 v[14:17], v[142:145], v[198:201], v[14:17]
	v_mfma_f32_16x16x32_bf16 v[10:13], v[150:153], v[198:201], v[10:13]
	v_mfma_f32_16x16x32_bf16 v[62:65], v[146:149], v[178:181], v[62:65]
	v_mfma_f32_16x16x32_bf16 v[58:61], v[154:157], v[178:181], v[58:61]
	v_mfma_f32_16x16x32_bf16 v[46:49], v[146:149], v[186:189], v[46:49]
	v_mfma_f32_16x16x32_bf16 v[42:45], v[154:157], v[186:189], v[42:45]
	v_mfma_f32_16x16x32_bf16 v[30:33], v[146:149], v[194:197], v[30:33]
	v_mfma_f32_16x16x32_bf16 v[26:29], v[154:157], v[194:197], v[26:29]
	v_mfma_f32_16x16x32_bf16 v[14:17], v[146:149], v[206:209], v[14:17]
	v_mfma_f32_16x16x32_bf16 v[10:13], v[154:157], v[206:209], v[10:13]
	v_mfma_f32_16x16x32_bf16 v[54:57], v[158:161], v[174:177], v[54:57]
	v_mfma_f32_16x16x32_bf16 v[50:53], v[166:169], v[174:177], v[50:53]
	v_mfma_f32_16x16x32_bf16 v[38:41], v[158:161], v[182:185], v[38:41]
	v_mfma_f32_16x16x32_bf16 v[34:37], v[166:169], v[182:185], v[34:37]
	v_mfma_f32_16x16x32_bf16 v[22:25], v[158:161], v[190:193], v[22:25]
	v_mfma_f32_16x16x32_bf16 v[18:21], v[166:169], v[190:193], v[18:21]
	v_mfma_f32_16x16x32_bf16 v[6:9], v[158:161], v[198:201], v[6:9]
	v_mfma_f32_16x16x32_bf16 v[2:5], v[166:169], v[198:201], v[2:5]
	v_mfma_f32_16x16x32_bf16 v[54:57], v[162:165], v[178:181], v[54:57]
	v_mfma_f32_16x16x32_bf16 v[50:53], v[170:173], v[178:181], v[50:53]
	v_mfma_f32_16x16x32_bf16 v[38:41], v[162:165], v[186:189], v[38:41]
	v_mfma_f32_16x16x32_bf16 v[34:37], v[170:173], v[186:189], v[34:37]
	v_mfma_f32_16x16x32_bf16 v[22:25], v[162:165], v[194:197], v[22:25]
	v_mfma_f32_16x16x32_bf16 v[18:21], v[170:173], v[194:197], v[18:21]
	v_mfma_f32_16x16x32_bf16 v[6:9], v[162:165], v[206:209], v[6:9]
	v_mfma_f32_16x16x32_bf16 v[2:5], v[170:173], v[206:209], v[2:5]
	s_setprio 0
	s_barrier
	s_add_i32 s39, 0, 0x18000
	s_add_i32 s40, 0, 0x1c000
	v_add_u32_e32 v154, s39, v140
	v_add_u32_e32 v170, s40, v140
	ds_read_b128 v[142:145], v154
	ds_read_b128 v[146:149], v154 offset:1024
	ds_read_b128 v[150:153], v154 offset:2048
	ds_read_b128 v[154:157], v154 offset:3072
	ds_read_b128 v[158:161], v170
	ds_read_b128 v[162:165], v170 offset:1024
	ds_read_b128 v[166:169], v170 offset:2048
	ds_read_b128 v[170:173], v170 offset:3072
	s_add_u32 s20, s20, 0x40000
	s_addc_u32 s21, s21, 0
	s_mov_b32 m0, s27
	v_lshl_add_u64 v[218:219], s[20:21], 0, v[134:135]
	ds_read_b128 v[174:177], v141 offset:32768
	ds_read_b128 v[178:181], v141 offset:33792
	ds_read_b128 v[182:185], v141 offset:34816
	ds_read_b128 v[186:189], v141 offset:35840
	ds_read_b128 v[190:193], v141 offset:36864
	ds_read_b128 v[194:197], v141 offset:37888
	ds_read_b128 v[198:201], v141 offset:38912
	ds_read_b128 v[206:209], v141 offset:39936
	global_load_lds_dwordx4 v[218:219], off
	v_lshl_add_u64 v[218:219], s[20:21], 0, v[132:133]
	s_mov_b32 m0, s28
	s_nop 0
	global_load_lds_dwordx4 v[218:219], off
	s_waitcnt vmcnt(8)
	s_waitcnt lgkmcnt(0)
	s_barrier
	s_setprio 1
	s_waitcnt lgkmcnt(0)
	v_mfma_f32_16x16x32_bf16 v[126:129], v[142:145], v[174:177], v[126:129]
	v_mfma_f32_16x16x32_bf16 v[122:125], v[150:153], v[174:177], v[122:125]
	v_mfma_f32_16x16x32_bf16 v[110:113], v[142:145], v[182:185], v[110:113]
	v_mfma_f32_16x16x32_bf16 v[106:109], v[150:153], v[182:185], v[106:109]
	v_mfma_f32_16x16x32_bf16 v[94:97], v[142:145], v[190:193], v[94:97]
	v_mfma_f32_16x16x32_bf16 v[90:93], v[150:153], v[190:193], v[90:93]
	v_mfma_f32_16x16x32_bf16 v[78:81], v[142:145], v[198:201], v[78:81]
	v_mfma_f32_16x16x32_bf16 v[74:77], v[150:153], v[198:201], v[74:77]
	v_mfma_f32_16x16x32_bf16 v[126:129], v[146:149], v[178:181], v[126:129]
	v_mfma_f32_16x16x32_bf16 v[122:125], v[154:157], v[178:181], v[122:125]
	v_mfma_f32_16x16x32_bf16 v[110:113], v[146:149], v[186:189], v[110:113]
	v_mfma_f32_16x16x32_bf16 v[106:109], v[154:157], v[186:189], v[106:109]
	v_mfma_f32_16x16x32_bf16 v[94:97], v[146:149], v[194:197], v[94:97]
	v_mfma_f32_16x16x32_bf16 v[90:93], v[154:157], v[194:197], v[90:93]
	v_mfma_f32_16x16x32_bf16 v[78:81], v[146:149], v[206:209], v[78:81]
	v_mfma_f32_16x16x32_bf16 v[74:77], v[154:157], v[206:209], v[74:77]
	v_mfma_f32_16x16x32_bf16 v[118:121], v[158:161], v[174:177], v[118:121]
	v_mfma_f32_16x16x32_bf16 v[114:117], v[166:169], v[174:177], v[114:117]
	v_mfma_f32_16x16x32_bf16 v[102:105], v[158:161], v[182:185], v[102:105]
	v_mfma_f32_16x16x32_bf16 v[98:101], v[166:169], v[182:185], v[98:101]
	v_mfma_f32_16x16x32_bf16 v[86:89], v[158:161], v[190:193], v[86:89]
	v_mfma_f32_16x16x32_bf16 v[82:85], v[166:169], v[190:193], v[82:85]
	v_mfma_f32_16x16x32_bf16 v[70:73], v[158:161], v[198:201], v[70:73]
	v_mfma_f32_16x16x32_bf16 v[66:69], v[166:169], v[198:201], v[66:69]
	v_mfma_f32_16x16x32_bf16 v[118:121], v[162:165], v[178:181], v[118:121]
	v_mfma_f32_16x16x32_bf16 v[114:117], v[170:173], v[178:181], v[114:117]
	v_mfma_f32_16x16x32_bf16 v[102:105], v[162:165], v[186:189], v[102:105]
	v_mfma_f32_16x16x32_bf16 v[98:101], v[170:173], v[186:189], v[98:101]
	v_mfma_f32_16x16x32_bf16 v[86:89], v[162:165], v[194:197], v[86:89]
	v_mfma_f32_16x16x32_bf16 v[82:85], v[170:173], v[194:197], v[82:85]
	v_mfma_f32_16x16x32_bf16 v[70:73], v[162:165], v[206:209], v[70:73]
	v_mfma_f32_16x16x32_bf16 v[66:69], v[170:173], v[206:209], v[66:69]
	s_setprio 0
	s_barrier
; #define PG8_STAGE(bufoff, gbase, voff) do { _Pragma("unroll") for (int _i = 0; _i < 2; ++_i) \
;         __builtin_amdgcn_global_load_lds((const unsigned*)((const char*)(gbase) + (voff)[_i]), (PG8_LAS unsigned*)(lds + (bufoff) + ldsw + _i * 8192), 16, 0, 0); } while (0)
; #define PG8_LDA(dst, b, h) do { _Pragma("unroll") for (int m = 0; m < 4; ++m) _Pragma("unroll") for (int k = 0; k < 2; ++k) dst[m][k] = *(const PG8_LAS bf16x8*)(lds + PG8_SA(b, h) + aoff + m * 2048 + k * 1024); } while (0)
; #define PG8_MMA(ai, bj, At, Bt) do { __builtin_amdgcn_s_setprio(1); _Pragma("unroll") for (int m = 0; m < 4; ++m) _Pragma("unroll") for (int n = 0; n < 2; ++n) _Pragma("unroll") for (int k = 0; k < 2; ++k) \
;         acc[ai][bj][m][n] = __builtin_amdgcn_mfma_f32_16x16x32_bf16(Bt[n][k], At[m][k], acc[ai][bj][m][n], 0, 0, 0); __builtin_amdgcn_s_setprio(0); } while (0)
; #define PG8_WAIT_V(n) asm volatile("s_waitcnt vmcnt(" #n ")" ::: "memory")
; #define PG8_WAIT_L(n) asm volatile("s_waitcnt lgkmcnt(" #n ")" ::: "memory")
; #define PG8_BAR __builtin_amdgcn_s_barrier()
; #define PG8_SCHED __builtin_amdgcn_sched_barrier(0)
; template <class Epi, class Sched, bool ALIGN_EPI = false, bool SP2 = false>
; __device__ __forceinline__ void gemm_phase(PG8_LAS unsigned char* lds, const Gemm g, const Sched& S, const Epi& E) {
;     ...
;         for (int t = 0; t < nt; t += 2) {
;             const bool last = (t == nt - 2);
;             const char* a1 = cA + (size_t)(t + 1) * kstep;
;             const char* a2 = last ? nA : cA + (size_t)(t + 2) * kstep; const char* b2 = last ? nB : cB + (size_t)(t + 2) * kstep;
;     ...
;             PG8_LDA(At, 1, 1); PG8_STAGE(PG8_SB(1, 0), b3, voffB); PG8_STAGE(PG8_SB(1, 1), b3 + hstep, voffB); PG8_STAGE(PG8_SA(1, 0), a3, voffA);
;             PG8_WAIT_V(8); PG8_WAIT_L(0); PG8_BAR; PG8_MMA(1, 0, At, B0); PG8_MMA(1, 1, At, B1); PG8_BAR; PG8_SCHED;
	s_add_i32 s20, s39, s23
	v_lshl_add_u64 v[210:211], v[210:211], 0, s[48:49]
	s_mov_b32 m0, s20
	ds_read_b128 v[174:177], v141 offset:49152
	ds_read_b128 v[178:181], v141 offset:50176
	ds_read_b128 v[182:185], v141 offset:51200
	ds_read_b128 v[186:189], v141 offset:52224
	ds_read_b128 v[190:193], v141 offset:53248
	ds_read_b128 v[194:197], v141 offset:54272
	ds_read_b128 v[198:201], v141 offset:55296
	ds_read_b128 v[206:209], v141 offset:56320
	global_load_lds_dwordx4 v[210:211], off
	s_add_i32 m0, s20, 0x2000
	s_add_u32 s18, s18, 0x40080
	v_lshl_add_u64 v[210:211], v[212:213], 0, s[48:49]
	s_addc_u32 s19, s19, 0
	s_add_i32 s20, s40, s23
	global_load_lds_dwordx4 v[210:211], off
	v_lshl_add_u64 v[210:211], s[18:19], 0, v[0:1]
	s_mov_b32 m0, s20
	s_nop 0
	global_load_lds_dwordx4 v[210:211], off
	v_lshl_add_u64 v[210:211], s[18:19], 0, v[130:131]
	s_add_i32 m0, s20, 0x2000
	s_nop 0
	global_load_lds_dwordx4 v[210:211], off
	v_lshl_add_u64 v[210:211], v[214:215], 0, s[48:49]
	s_mov_b32 m0, s29
	s_nop 0
	global_load_lds_dwordx4 v[210:211], off
	v_lshl_add_u64 v[210:211], v[216:217], 0, s[48:49]
	s_mov_b32 m0, s30
	s_nop 0
	global_load_lds_dwordx4 v[210:211], off
	s_waitcnt vmcnt(8)
	s_waitcnt lgkmcnt(0)
	s_barrier
	s_setprio 1
	s_waitcnt lgkmcnt(0)
	v_mfma_f32_16x16x32_bf16 v[62:65], v[142:145], v[174:177], v[62:65]
	v_mfma_f32_16x16x32_bf16 v[58:61], v[150:153], v[174:177], v[58:61]
	v_mfma_f32_16x16x32_bf16 v[46:49], v[142:145], v[182:185], v[46:49]
	v_mfma_f32_16x16x32_bf16 v[42:45], v[150:153], v[182:185], v[42:45]
	v_mfma_f32_16x16x32_bf16 v[30:33], v[142:145], v[190:193], v[30:33]
	v_mfma_f32_16x16x32_bf16 v[26:29], v[150:153], v[190:193], v[26:29]
	v_mfma_f32_16x16x32_bf16 v[14:17], v[142:145], v[198:201], v[14:17]
	v_mfma_f32_16x16x32_bf16 v[10:13], v[150:153], v[198:201], v[10:13]
	v_mfma_f32_16x16x32_bf16 v[62:65], v[146:149], v[178:181], v[62:65]
	v_mfma_f32_16x16x32_bf16 v[58:61], v[154:157], v[178:181], v[58:61]
	v_mfma_f32_16x16x32_bf16 v[46:49], v[146:149], v[186:189], v[46:49]
	v_mfma_f32_16x16x32_bf16 v[42:45], v[154:157], v[186:189], v[42:45]
	v_mfma_f32_16x16x32_bf16 v[30:33], v[146:149], v[194:197], v[30:33]
	v_mfma_f32_16x16x32_bf16 v[26:29], v[154:157], v[194:197], v[26:29]
	v_mfma_f32_16x16x32_bf16 v[14:17], v[146:149], v[206:209], v[14:17]
	v_mfma_f32_16x16x32_bf16 v[10:13], v[154:157], v[206:209], v[10:13]
	v_mfma_f32_16x16x32_bf16 v[54:57], v[158:161], v[174:177], v[54:57]
	v_mfma_f32_16x16x32_bf16 v[50:53], v[166:169], v[174:177], v[50:53]
	v_mfma_f32_16x16x32_bf16 v[38:41], v[158:161], v[182:185], v[38:41]
	v_mfma_f32_16x16x32_bf16 v[34:37], v[166:169], v[182:185], v[34:37]
	v_mfma_f32_16x16x32_bf16 v[22:25], v[158:161], v[190:193], v[22:25]
	v_mfma_f32_16x16x32_bf16 v[18:21], v[166:169], v[190:193], v[18:21]
	v_mfma_f32_16x16x32_bf16 v[6:9], v[158:161], v[198:201], v[6:9]
	v_mfma_f32_16x16x32_bf16 v[2:5], v[166:169], v[198:201], v[2:5]
	v_mfma_f32_16x16x32_bf16 v[54:57], v[162:165], v[178:181], v[54:57]
	v_mfma_f32_16x16x32_bf16 v[50:53], v[170:173], v[178:181], v[50:53]
	v_mfma_f32_16x16x32_bf16 v[38:41], v[162:165], v[186:189], v[38:41]
	v_mfma_f32_16x16x32_bf16 v[34:37], v[170:173], v[186:189], v[34:37]
	v_mfma_f32_16x16x32_bf16 v[22:25], v[162:165], v[194:197], v[22:25]
	v_mfma_f32_16x16x32_bf16 v[18:21], v[170:173], v[194:197], v[18:21]
	v_mfma_f32_16x16x32_bf16 v[6:9], v[162:165], v[206:209], v[6:9]
	v_mfma_f32_16x16x32_bf16 v[2:5], v[170:173], v[206:209], v[2:5]
	s_setprio 0
	s_barrier
	s_add_i32 s38, s38, 2
	s_add_u32 s16, s16, 0x100
	s_addc_u32 s17, s17, 0
	s_add_u32 s36, s36, 0x100
	s_addc_u32 s37, s37, 0
	s_cmp_gt_u32 s38, 13
	s_cbranch_scc0 .LBB0_71
	s_and_b64 vcc, exec, s[4:5]
	s_cbranch_vccz .LBB0_74
	s_barrier

; #define PG8_STAGE(bufoff, gbase, voff) do { _Pragma("unroll") for (int _i = 0; _i < 2; ++_i) \
;         __builtin_amdgcn_global_load_lds((const unsigned*)((const char*)(gbase) + (voff)[_i]), (PG8_LAS unsigned*)(lds + (bufoff) + ldsw + _i * 8192), 16, 0, 0); } while (0)
; #define PG8_LDA(dst, b, h) do { _Pragma("unroll") for (int m = 0; m < 4; ++m) _Pragma("unroll") for (int k = 0; k < 2; ++k) dst[m][k] = *(const PG8_LAS bf16x8*)(lds + PG8_SA(b, h) + aoff + m * 2048 + k * 1024); } while (0)
; #define PG8_LDB(dst, b, h) do { _Pragma("unroll") for (int n = 0; n < 2; ++n) _Pragma("unroll") for (int k = 0; k < 2; ++k) dst[n][k] = *(const PG8_LAS bf16x8*)(lds + PG8_SB(b, h) + boff + n * 2048 + k * 1024); } while (0)
; #define PG8_MMA(ai, bj, At, Bt) do { __builtin_amdgcn_s_setprio(1); _Pragma("unroll") for (int m = 0; m < 4; ++m) _Pragma("unroll") for (int n = 0; n < 2; ++n) _Pragma("unroll") for (int k = 0; k < 2; ++k) \
;         acc[ai][bj][m][n] = __builtin_amdgcn_mfma_f32_16x16x32_bf16(Bt[n][k], At[m][k], acc[ai][bj][m][n], 0, 0, 0); __builtin_amdgcn_s_setprio(0); } while (0)
; #define PG8_WAIT_V(n) asm volatile("s_waitcnt vmcnt(" #n ")" ::: "memory")
; #define PG8_WAIT_L(n) asm volatile("s_waitcnt lgkmcnt(" #n ")" ::: "memory")
; #define PG8_BAR __builtin_amdgcn_s_barrier()
; #define PG8_SCHED __builtin_amdgcn_sched_barrier(0)
; template <class Epi, class Sched, bool ALIGN_EPI = false, bool SP2 = false>
; __device__ __forceinline__ void gemm_phase(PG8_LAS unsigned char* lds, const Gemm g, const Sched& S, const Epi& E) {
;     ...
;         for (int t = 0; t < nt; t += 2) {
;             const bool last = (t == nt - 2);
;             const char* a1 = cA + (size_t)(t + 1) * kstep;
;             const char* a2 = last ? nA : cA + (size_t)(t + 2) * kstep; const char* b2 = last ? nB : cB + (size_t)(t + 2) * kstep;
;             const char* a3 = a2 + kstep; const char* b3 = b2 + kstep;
;             if (last && has_next) S.a_ready(nxt);
;             if constexpr (SP2) {
;             PG8_LDB(B0, 0, 0); PG8_LDB(B1, 0, 1); PG8_SCHED; PG8_LDA(At, 0, 0); PG8_STAGE(PG8_SA(1, 1), a1 + hstep, voffA);
;             PG8_WAIT_V(8); PG8_WAIT_L(0); PG8_BAR; PG8_MMA(0, 0, At, B0); PG8_MMA(0, 1, At, B1); PG8_BAR; PG8_SCHED;
;             PG8_LDA(At, 0, 1); PG8_STAGE(PG8_SB(0, 0), b2, voffB); PG8_STAGE(PG8_SB(0, 1), b2 + hstep, voffB); PG8_STAGE(PG8_SA(0, 0), a2, voffA);
.LBB0_147:
	s_add_u32 s6, s4, 0xfffc0080
	s_addc_u32 s7, s5, -1
	s_cmp_eq_u32 s39, 12
	s_cselect_b32 s9, s11, s7
	s_cselect_b32 s8, s19, s6
	s_cselect_b32 s7, s27, s38
	s_cselect_b32 s6, s29, s31
	s_add_i32 s40, 0, 0x10000
	v_add_u32_e32 v0, s40, v176
	s_add_i32 s44, 0, 0x14000
	ds_read_b128 v[58:61], v0
	ds_read_b128 v[62:65], v0 offset:1024
	ds_read_b128 v[66:69], v0 offset:2048
	ds_read_b128 v[70:73], v0 offset:3072
	v_add_u32_e32 v0, s44, v176
	ds_read_b128 v[74:77], v0
	ds_read_b128 v[78:81], v0 offset:1024
	ds_read_b128 v[82:85], v0 offset:2048
	ds_read_b128 v[172:175], v0 offset:3072
	v_lshl_add_u64 v[86:87], s[4:5], 0, v[168:169]
	s_add_i32 m0, s12, 0xc000
	ds_read_b128 v[178:181], v177
	ds_read_b128 v[182:185], v177 offset:1024
	ds_read_b128 v[186:189], v177 offset:2048
	ds_read_b128 v[190:193], v177 offset:3072
	ds_read_b128 v[194:197], v177 offset:4096
	ds_read_b128 v[198:201], v177 offset:5120
	ds_read_b128 v[206:209], v177 offset:6144
	ds_read_b128 v[210:213], v177 offset:7168
	global_load_lds_dwordx4 v[86:87], off
	v_lshl_add_u64 v[86:87], s[4:5], 0, v[170:171]
	s_add_i32 m0, s12, 0xe000
	s_nop 0
	global_load_lds_dwordx4 v[86:87], off
	s_waitcnt vmcnt(8)
	s_waitcnt lgkmcnt(0)
	s_barrier
	s_setprio 1
	s_waitcnt lgkmcnt(0)
	v_mfma_f32_16x16x32_bf16 v[156:159], v[58:61], v[178:181], v[156:159]
	v_mfma_f32_16x16x32_bf16 v[152:155], v[66:69], v[178:181], v[152:155]
	v_mfma_f32_16x16x32_bf16 v[140:143], v[58:61], v[186:189], v[140:143]
	v_mfma_f32_16x16x32_bf16 v[136:139], v[66:69], v[186:189], v[136:139]
	v_mfma_f32_16x16x32_bf16 v[124:127], v[58:61], v[194:197], v[124:127]
	v_mfma_f32_16x16x32_bf16 v[120:123], v[66:69], v[194:197], v[120:123]
	v_mfma_f32_16x16x32_bf16 v[108:111], v[58:61], v[206:209], v[108:111]
	v_mfma_f32_16x16x32_bf16 v[104:107], v[66:69], v[206:209], v[104:107]
	v_mfma_f32_16x16x32_bf16 v[156:159], v[62:65], v[182:185], v[156:159]
	v_mfma_f32_16x16x32_bf16 v[152:155], v[70:73], v[182:185], v[152:155]
	v_mfma_f32_16x16x32_bf16 v[140:143], v[62:65], v[190:193], v[140:143]
	v_mfma_f32_16x16x32_bf16 v[136:139], v[70:73], v[190:193], v[136:139]
	v_mfma_f32_16x16x32_bf16 v[124:127], v[62:65], v[198:201], v[124:127]
	v_mfma_f32_16x16x32_bf16 v[120:123], v[70:73], v[198:201], v[120:123]
	v_mfma_f32_16x16x32_bf16 v[108:111], v[62:65], v[210:213], v[108:111]
	v_mfma_f32_16x16x32_bf16 v[104:107], v[70:73], v[210:213], v[104:107]
	v_mfma_f32_16x16x32_bf16 v[148:151], v[74:77], v[178:181], v[148:151]
	v_mfma_f32_16x16x32_bf16 v[144:147], v[82:85], v[178:181], v[144:147]
	v_mfma_f32_16x16x32_bf16 v[132:135], v[74:77], v[186:189], v[132:135]
	v_mfma_f32_16x16x32_bf16 v[128:131], v[82:85], v[186:189], v[128:131]
	v_mfma_f32_16x16x32_bf16 v[116:119], v[74:77], v[194:197], v[116:119]
	v_mfma_f32_16x16x32_bf16 v[112:115], v[82:85], v[194:197], v[112:115]
	v_mfma_f32_16x16x32_bf16 v[100:103], v[74:77], v[206:209], v[100:103]
	v_mfma_f32_16x16x32_bf16 v[96:99], v[82:85], v[206:209], v[96:99]
	v_mfma_f32_16x16x32_bf16 v[148:151], v[78:81], v[182:185], v[148:151]
	v_mfma_f32_16x16x32_bf16 v[144:147], v[172:175], v[182:185], v[144:147]
	v_mfma_f32_16x16x32_bf16 v[132:135], v[78:81], v[190:193], v[132:135]
	v_mfma_f32_16x16x32_bf16 v[128:131], v[172:175], v[190:193], v[128:131]
	v_mfma_f32_16x16x32_bf16 v[116:119], v[78:81], v[198:201], v[116:119]
	v_mfma_f32_16x16x32_bf16 v[112:115], v[172:175], v[198:201], v[112:115]
	v_mfma_f32_16x16x32_bf16 v[100:103], v[78:81], v[210:213], v[100:103]
	v_mfma_f32_16x16x32_bf16 v[96:99], v[172:175], v[210:213], v[96:99]
	s_setprio 0
	s_barrier
	s_add_i32 s40, s40, s2
	v_lshl_add_u64 v[214:215], s[6:7], 0, v[164:165]
	s_mov_b32 m0, s40
	ds_read_b128 v[178:181], v177 offset:16384
	ds_read_b128 v[182:185], v177 offset:17408
	ds_read_b128 v[186:189], v177 offset:18432
	ds_read_b128 v[190:193], v177 offset:19456
	ds_read_b128 v[194:197], v177 offset:20480
	ds_read_b128 v[198:201], v177 offset:21504
	ds_read_b128 v[206:209], v177 offset:22528
	ds_read_b128 v[210:213], v177 offset:23552
	global_load_lds_dwordx4 v[214:215], off
	s_add_i32 m0, s40, 0x2000
	s_add_u32 s40, s6, 0x40000
	v_lshl_add_u64 v[216:217], s[6:7], 0, v[160:161]
	s_addc_u32 s41, s7, 0
	s_add_i32 s44, s44, s2
	global_load_lds_dwordx4 v[216:217], off
	v_lshl_add_u64 v[86:87], s[40:41], 0, v[164:165]
	s_mov_b32 m0, s44
	v_lshl_add_u64 v[218:219], s[8:9], 0, v[166:167]
	global_load_lds_dwordx4 v[86:87], off
	v_lshl_add_u64 v[86:87], s[40:41], 0, v[160:161]
	s_add_i32 m0, s44, 0x2000
	v_lshl_add_u64 v[220:221], s[8:9], 0, v[162:163]
	global_load_lds_dwordx4 v[86:87], off
	s_mov_b32 m0, s12
	s_nop 0
	global_load_lds_dwordx4 v[218:219], off
	s_mov_b32 m0, s13
	s_nop 0
	global_load_lds_dwordx4 v[220:221], off
	s_waitcnt vmcnt(8)
	s_waitcnt lgkmcnt(0)
	s_barrier
; #define PG8_STAGE(bufoff, gbase, voff) do { _Pragma("unroll") for (int _i = 0; _i < 2; ++_i) \
;         __builtin_amdgcn_global_load_lds((const unsigned*)((const char*)(gbase) + (voff)[_i]), (PG8_LAS unsigned*)(lds + (bufoff) + ldsw + _i * 8192), 16, 0, 0); } while (0)
; #define PG8_LDA(dst, b, h) do { _Pragma("unroll") for (int m = 0; m < 4; ++m) _Pragma("unroll") for (int k = 0; k < 2; ++k) dst[m][k] = *(const PG8_LAS bf16x8*)(lds + PG8_SA(b, h) + aoff + m * 2048 + k * 1024); } while (0)
; #define PG8_LDB(dst, b, h) do { _Pragma("unroll") for (int n = 0; n < 2; ++n) _Pragma("unroll") for (int k = 0; k < 2; ++k) dst[n][k] = *(const PG8_LAS bf16x8*)(lds + PG8_SB(b, h) + boff + n * 2048 + k * 1024); } while (0)
; #define PG8_MMA(ai, bj, At, Bt) do { __builtin_amdgcn_s_setprio(1); _Pragma("unroll") for (int m = 0; m < 4; ++m) _Pragma("unroll") for (int n = 0; n < 2; ++n) _Pragma("unroll") for (int k = 0; k < 2; ++k) \
;         acc[ai][bj][m][n] = __builtin_amdgcn_mfma_f32_16x16x32_bf16(Bt[n][k], At[m][k], acc[ai][bj][m][n], 0, 0, 0); __builtin_amdgcn_s_setprio(0); } while (0)
; #define PG8_WAIT_V(n) asm volatile("s_waitcnt vmcnt(" #n ")" ::: "memory")
; #define PG8_WAIT_L(n) asm volatile("s_waitcnt lgkmcnt(" #n ")" ::: "memory")
; #define PG8_BAR __builtin_amdgcn_s_barrier()
; #define PG8_SCHED __builtin_amdgcn_sched_barrier(0)
; template <class Epi, class Sched, bool ALIGN_EPI = false, bool SP2 = false>
; __device__ __forceinline__ void gemm_phase(PG8_LAS unsigned char* lds, const Gemm g, const Sched& S, const Epi& E) {
;     ...
;             PG8_WAIT_V(8); PG8_WAIT_L(0); PG8_BAR; PG8_MMA(1, 0, At, B0); PG8_MMA(1, 1, At, B1); PG8_BAR; PG8_SCHED;
;             PG8_LDB(B0, 1, 0); PG8_LDB(B1, 1, 1); PG8_SCHED; PG8_LDA(At, 1, 0); PG8_STAGE(PG8_SA(0, 1), a2 + hstep, voffA);
;             PG8_WAIT_V(8); PG8_WAIT_L(0); PG8_BAR; PG8_MMA(0, 0, At, B0); PG8_MMA(0, 1, At, B1); PG8_BAR; PG8_SCHED;
	s_setprio 1
	s_waitcnt lgkmcnt(0)
	v_mfma_f32_16x16x32_bf16 v[92:95], v[58:61], v[178:181], v[92:95]
	v_mfma_f32_16x16x32_bf16 v[86:89], v[66:69], v[178:181], v[88:91]
	v_mfma_f32_16x16x32_bf16 v[46:49], v[58:61], v[186:189], v[46:49]
	v_mfma_f32_16x16x32_bf16 v[42:45], v[66:69], v[186:189], v[42:45]
	v_mfma_f32_16x16x32_bf16 v[30:33], v[58:61], v[194:197], v[30:33]
	v_mfma_f32_16x16x32_bf16 v[26:29], v[66:69], v[194:197], v[26:29]
	v_mfma_f32_16x16x32_bf16 v[14:17], v[58:61], v[206:209], v[14:17]
	v_mfma_f32_16x16x32_bf16 v[10:13], v[66:69], v[206:209], v[10:13]
	v_mfma_f32_16x16x32_bf16 v[92:95], v[62:65], v[182:185], v[92:95]
	v_mfma_f32_16x16x32_bf16 v[86:89], v[70:73], v[182:185], v[86:89]
	v_mfma_f32_16x16x32_bf16 v[46:49], v[62:65], v[190:193], v[46:49]
	v_mfma_f32_16x16x32_bf16 v[42:45], v[70:73], v[190:193], v[42:45]
	v_mfma_f32_16x16x32_bf16 v[30:33], v[62:65], v[198:201], v[30:33]
	v_mfma_f32_16x16x32_bf16 v[26:29], v[70:73], v[198:201], v[26:29]
	v_mfma_f32_16x16x32_bf16 v[14:17], v[62:65], v[210:213], v[14:17]
	v_mfma_f32_16x16x32_bf16 v[10:13], v[70:73], v[210:213], v[10:13]
	v_mfma_f32_16x16x32_bf16 v[54:57], v[74:77], v[178:181], v[54:57]
	v_mfma_f32_16x16x32_bf16 v[50:53], v[82:85], v[178:181], v[50:53]
	v_mfma_f32_16x16x32_bf16 v[38:41], v[74:77], v[186:189], v[38:41]
	v_mfma_f32_16x16x32_bf16 v[34:37], v[82:85], v[186:189], v[34:37]
	v_mfma_f32_16x16x32_bf16 v[22:25], v[74:77], v[194:197], v[22:25]
	v_mfma_f32_16x16x32_bf16 v[18:21], v[82:85], v[194:197], v[18:21]
	v_mfma_f32_16x16x32_bf16 v[6:9], v[74:77], v[206:209], v[6:9]
	v_mfma_f32_16x16x32_bf16 v[2:5], v[82:85], v[206:209], v[2:5]
	v_mfma_f32_16x16x32_bf16 v[54:57], v[78:81], v[182:185], v[54:57]
	v_mfma_f32_16x16x32_bf16 v[50:53], v[172:175], v[182:185], v[50:53]
	v_mfma_f32_16x16x32_bf16 v[38:41], v[78:81], v[190:193], v[38:41]
	v_mfma_f32_16x16x32_bf16 v[34:37], v[172:175], v[190:193], v[34:37]
	v_mfma_f32_16x16x32_bf16 v[22:25], v[78:81], v[198:201], v[22:25]
	v_mfma_f32_16x16x32_bf16 v[18:21], v[172:175], v[198:201], v[18:21]
	v_mfma_f32_16x16x32_bf16 v[6:9], v[78:81], v[210:213], v[6:9]
	v_mfma_f32_16x16x32_bf16 v[2:5], v[172:175], v[210:213], v[2:5]
	s_setprio 0
	s_barrier
	s_add_i32 s40, 0, 0x18000
	v_add_u32_e32 v0, s40, v176
	s_add_i32 s41, 0, 0x1c000
	ds_read_b128 v[58:61], v0
	ds_read_b128 v[62:65], v0 offset:1024
	ds_read_b128 v[66:69], v0 offset:2048
	ds_read_b128 v[70:73], v0 offset:3072
	v_add_u32_e32 v0, s41, v176
	ds_read_b128 v[74:77], v0
	ds_read_b128 v[78:81], v0 offset:1024
	ds_read_b128 v[82:85], v0 offset:2048
	ds_read_b128 v[172:175], v0 offset:3072
	s_add_u32 s8, s8, 0x40000
	s_addc_u32 s9, s9, 0
	s_mov_b32 m0, s14
	v_lshl_add_u64 v[90:91], s[8:9], 0, v[166:167]
	ds_read_b128 v[178:181], v177 offset:32768
	ds_read_b128 v[182:185], v177 offset:33792
	ds_read_b128 v[186:189], v177 offset:34816
	ds_read_b128 v[190:193], v177 offset:35840
	ds_read_b128 v[194:197], v177 offset:36864
	ds_read_b128 v[198:201], v177 offset:37888
	ds_read_b128 v[206:209], v177 offset:38912
	ds_read_b128 v[210:213], v177 offset:39936
	global_load_lds_dwordx4 v[90:91], off
	v_lshl_add_u64 v[90:91], s[8:9], 0, v[162:163]
	s_mov_b32 m0, s15
	s_nop 0
	global_load_lds_dwordx4 v[90:91], off
	s_waitcnt vmcnt(8)
	s_waitcnt lgkmcnt(0)
	s_barrier
	s_setprio 1
	s_waitcnt lgkmcnt(0)
	v_mfma_f32_16x16x32_bf16 v[156:159], v[58:61], v[178:181], v[156:159]
	v_mfma_f32_16x16x32_bf16 v[152:155], v[66:69], v[178:181], v[152:155]
	v_mfma_f32_16x16x32_bf16 v[140:143], v[58:61], v[186:189], v[140:143]
	v_mfma_f32_16x16x32_bf16 v[136:139], v[66:69], v[186:189], v[136:139]
	v_mfma_f32_16x16x32_bf16 v[124:127], v[58:61], v[194:197], v[124:127]
	v_mfma_f32_16x16x32_bf16 v[120:123], v[66:69], v[194:197], v[120:123]
	v_mfma_f32_16x16x32_bf16 v[108:111], v[58:61], v[206:209], v[108:111]
	v_mfma_f32_16x16x32_bf16 v[104:107], v[66:69], v[206:209], v[104:107]
	v_mfma_f32_16x16x32_bf16 v[156:159], v[62:65], v[182:185], v[156:159]
	v_mfma_f32_16x16x32_bf16 v[152:155], v[70:73], v[182:185], v[152:155]
	v_mfma_f32_16x16x32_bf16 v[140:143], v[62:65], v[190:193], v[140:143]
	v_mfma_f32_16x16x32_bf16 v[136:139], v[70:73], v[190:193], v[136:139]
	v_mfma_f32_16x16x32_bf16 v[124:127], v[62:65], v[198:201], v[124:127]
	v_mfma_f32_16x16x32_bf16 v[120:123], v[70:73], v[198:201], v[120:123]
	v_mfma_f32_16x16x32_bf16 v[108:111], v[62:65], v[210:213], v[108:111]
	v_mfma_f32_16x16x32_bf16 v[104:107], v[70:73], v[210:213], v[104:107]
	v_mfma_f32_16x16x32_bf16 v[148:151], v[74:77], v[178:181], v[148:151]
	v_mfma_f32_16x16x32_bf16 v[144:147], v[82:85], v[178:181], v[144:147]
	v_mfma_f32_16x16x32_bf16 v[132:135], v[74:77], v[186:189], v[132:135]
	v_mfma_f32_16x16x32_bf16 v[128:131], v[82:85], v[186:189], v[128:131]
	v_mfma_f32_16x16x32_bf16 v[116:119], v[74:77], v[194:197], v[116:119]
	v_mfma_f32_16x16x32_bf16 v[112:115], v[82:85], v[194:197], v[112:115]
	v_mfma_f32_16x16x32_bf16 v[100:103], v[74:77], v[206:209], v[100:103]
	v_mfma_f32_16x16x32_bf16 v[96:99], v[82:85], v[206:209], v[96:99]
	v_mfma_f32_16x16x32_bf16 v[148:151], v[78:81], v[182:185], v[148:151]
	v_mfma_f32_16x16x32_bf16 v[144:147], v[172:175], v[182:185], v[144:147]
	v_mfma_f32_16x16x32_bf16 v[132:135], v[78:81], v[190:193], v[132:135]
	v_mfma_f32_16x16x32_bf16 v[128:131], v[172:175], v[190:193], v[128:131]
	v_mfma_f32_16x16x32_bf16 v[116:119], v[78:81], v[198:201], v[116:119]
	v_mfma_f32_16x16x32_bf16 v[112:115], v[172:175], v[198:201], v[112:115]
	v_mfma_f32_16x16x32_bf16 v[100:103], v[78:81], v[210:213], v[100:103]
	v_mfma_f32_16x16x32_bf16 v[96:99], v[172:175], v[210:213], v[96:99]
	s_setprio 0
	s_barrier
; #define PG8_STAGE(bufoff, gbase, voff) do { _Pragma("unroll") for (int _i = 0; _i < 2; ++_i) \
;         __builtin_amdgcn_global_load_lds((const unsigned*)((const char*)(gbase) + (voff)[_i]), (PG8_LAS unsigned*)(lds + (bufoff) + ldsw + _i * 8192), 16, 0, 0); } while (0)
; #define PG8_LDA(dst, b, h) do { _Pragma("unroll") for (int m = 0; m < 4; ++m) _Pragma("unroll") for (int k = 0; k < 2; ++k) dst[m][k] = *(const PG8_LAS bf16x8*)(lds + PG8_SA(b, h) + aoff + m * 2048 + k * 1024); } while (0)
; #define PG8_MMA(ai, bj, At, Bt) do { __builtin_amdgcn_s_setprio(1); _Pragma("unroll") for (int m = 0; m < 4; ++m) _Pragma("unroll") for (int n = 0; n < 2; ++n) _Pragma("unroll") for (int k = 0; k < 2; ++k) \
;         acc[ai][bj][m][n] = __builtin_amdgcn_mfma_f32_16x16x32_bf16(Bt[n][k], At[m][k], acc[ai][bj][m][n], 0, 0, 0); __builtin_amdgcn_s_setprio(0); } while (0)
; #define PG8_WAIT_V(n) asm volatile("s_waitcnt vmcnt(" #n ")" ::: "memory")
; #define PG8_WAIT_L(n) asm volatile("s_waitcnt lgkmcnt(" #n ")" ::: "memory")
; #define PG8_BAR __builtin_amdgcn_s_barrier()
; #define PG8_SCHED __builtin_amdgcn_sched_barrier(0)
; template <class Epi, class Sched, bool ALIGN_EPI = false, bool SP2 = false>
; __device__ __forceinline__ void gemm_phase(PG8_LAS unsigned char* lds, const Gemm g, const Sched& S, const Epi& E) {
;     ...
;             PG8_LDA(At, 1, 1); PG8_STAGE(PG8_SB(1, 0), b3, voffB); PG8_STAGE(PG8_SB(1, 1), b3 + hstep, voffB); PG8_STAGE(PG8_SA(1, 0), a3, voffA);
;             PG8_WAIT_V(8); PG8_WAIT_L(0); PG8_BAR; PG8_MMA(1, 0, At, B0); PG8_MMA(1, 1, At, B1); PG8_BAR; PG8_SCHED;
;     ...
;         if constexpr (ALIGN_EPI) { if (wr == 0) PG8_BAR; }
	s_add_i32 s8, s40, s2
	v_lshl_add_u64 v[90:91], v[214:215], 0, s[46:47]
	s_mov_b32 m0, s8
	ds_read_b128 v[178:181], v177 offset:49152
	ds_read_b128 v[182:185], v177 offset:50176
	ds_read_b128 v[186:189], v177 offset:51200
	ds_read_b128 v[190:193], v177 offset:52224
	ds_read_b128 v[194:197], v177 offset:53248
	ds_read_b128 v[198:201], v177 offset:54272
	ds_read_b128 v[206:209], v177 offset:55296
	ds_read_b128 v[210:213], v177 offset:56320
	global_load_lds_dwordx4 v[90:91], off
	s_add_i32 m0, s8, 0x2000
	s_add_u32 s6, s6, 0x40080
	v_lshl_add_u64 v[90:91], v[216:217], 0, s[46:47]
	s_addc_u32 s7, s7, 0
	s_add_i32 s8, s41, s2
	global_load_lds_dwordx4 v[90:91], off
	v_lshl_add_u64 v[90:91], s[6:7], 0, v[164:165]
	s_mov_b32 m0, s8
	s_nop 0
	global_load_lds_dwordx4 v[90:91], off
	v_lshl_add_u64 v[90:91], s[6:7], 0, v[160:161]
	s_add_i32 m0, s8, 0x2000
	s_nop 0
	global_load_lds_dwordx4 v[90:91], off
	v_lshl_add_u64 v[90:91], v[218:219], 0, s[46:47]
	s_mov_b32 m0, s16
	s_nop 0
	global_load_lds_dwordx4 v[90:91], off
	v_lshl_add_u64 v[90:91], v[220:221], 0, s[46:47]
	s_mov_b32 m0, s17
	s_nop 0
	global_load_lds_dwordx4 v[90:91], off
	s_waitcnt vmcnt(8)
	s_waitcnt lgkmcnt(0)
	s_barrier
	s_setprio 1
	s_waitcnt lgkmcnt(0)
	v_mfma_f32_16x16x32_bf16 v[90:93], v[58:61], v[178:181], v[92:95]
	v_mfma_f32_16x16x32_bf16 v[86:89], v[66:69], v[178:181], v[86:89]
	v_mfma_f32_16x16x32_bf16 v[46:49], v[58:61], v[186:189], v[46:49]
	v_mfma_f32_16x16x32_bf16 v[42:45], v[66:69], v[186:189], v[42:45]
	v_mfma_f32_16x16x32_bf16 v[30:33], v[58:61], v[194:197], v[30:33]
	v_mfma_f32_16x16x32_bf16 v[26:29], v[66:69], v[194:197], v[26:29]
	v_mfma_f32_16x16x32_bf16 v[14:17], v[58:61], v[206:209], v[14:17]
	v_mfma_f32_16x16x32_bf16 v[10:13], v[66:69], v[206:209], v[10:13]
	v_mfma_f32_16x16x32_bf16 v[92:95], v[62:65], v[182:185], v[90:93]
	v_mfma_f32_16x16x32_bf16 v[88:91], v[70:73], v[182:185], v[86:89]
	v_mfma_f32_16x16x32_bf16 v[46:49], v[62:65], v[190:193], v[46:49]
	v_mfma_f32_16x16x32_bf16 v[42:45], v[70:73], v[190:193], v[42:45]
	v_mfma_f32_16x16x32_bf16 v[30:33], v[62:65], v[198:201], v[30:33]
	v_mfma_f32_16x16x32_bf16 v[26:29], v[70:73], v[198:201], v[26:29]
	v_mfma_f32_16x16x32_bf16 v[14:17], v[62:65], v[210:213], v[14:17]
	v_mfma_f32_16x16x32_bf16 v[10:13], v[70:73], v[210:213], v[10:13]
	v_mfma_f32_16x16x32_bf16 v[54:57], v[74:77], v[178:181], v[54:57]
	v_mfma_f32_16x16x32_bf16 v[50:53], v[82:85], v[178:181], v[50:53]
	v_mfma_f32_16x16x32_bf16 v[38:41], v[74:77], v[186:189], v[38:41]
	v_mfma_f32_16x16x32_bf16 v[34:37], v[82:85], v[186:189], v[34:37]
	v_mfma_f32_16x16x32_bf16 v[22:25], v[74:77], v[194:197], v[22:25]
	v_mfma_f32_16x16x32_bf16 v[18:21], v[82:85], v[194:197], v[18:21]
	v_mfma_f32_16x16x32_bf16 v[6:9], v[74:77], v[206:209], v[6:9]
	v_mfma_f32_16x16x32_bf16 v[2:5], v[82:85], v[206:209], v[2:5]
	v_mfma_f32_16x16x32_bf16 v[54:57], v[78:81], v[182:185], v[54:57]
	v_mfma_f32_16x16x32_bf16 v[50:53], v[172:175], v[182:185], v[50:53]
	v_mfma_f32_16x16x32_bf16 v[38:41], v[78:81], v[190:193], v[38:41]
	v_mfma_f32_16x16x32_bf16 v[34:37], v[172:175], v[190:193], v[34:37]
	v_mfma_f32_16x16x32_bf16 v[22:25], v[78:81], v[198:201], v[22:25]
	v_mfma_f32_16x16x32_bf16 v[18:21], v[172:175], v[198:201], v[18:21]
	v_mfma_f32_16x16x32_bf16 v[6:9], v[78:81], v[210:213], v[6:9]
	v_mfma_f32_16x16x32_bf16 v[2:5], v[172:175], v[210:213], v[2:5]
	s_setprio 0
	s_barrier
	s_add_i32 s39, s39, 2
	s_add_u32 s4, s4, 0x100
	s_addc_u32 s5, s5, 0
	s_add_u32 s31, s31, 0x100
	s_addc_u32 s38, s38, 0
	s_cmp_gt_u32 s39, 13
	s_cbranch_scc0 .LBB0_147
	s_and_b64 vcc, exec, s[24:25]
	s_cbranch_vccz .LBB0_150
	s_barrier

; #define PG8_STAGE(bufoff, gbase, voff) do { _Pragma("unroll") for (int _i = 0; _i < 2; ++_i) \
;         __builtin_amdgcn_global_load_lds((const unsigned*)((const char*)(gbase) + (voff)[_i]), (PG8_LAS unsigned*)(lds + (bufoff) + ldsw + _i * 8192), 16, 0, 0); } while (0)
; #define PG8_LDA(dst, b, h) do { _Pragma("unroll") for (int m = 0; m < 4; ++m) _Pragma("unroll") for (int k = 0; k < 2; ++k) dst[m][k] = *(const PG8_LAS bf16x8*)(lds + PG8_SA(b, h) + aoff + m * 2048 + k * 1024); } while (0)
; #define PG8_LDB(dst, b, h) do { _Pragma("unroll") for (int n = 0; n < 2; ++n) _Pragma("unroll") for (int k = 0; k < 2; ++k) dst[n][k] = *(const PG8_LAS bf16x8*)(lds + PG8_SB(b, h) + boff + n * 2048 + k * 1024); } while (0)
; #define PG8_MMA(ai, bj, At, Bt) do { __builtin_amdgcn_s_setprio(1); _Pragma("unroll") for (int m = 0; m < 4; ++m) _Pragma("unroll") for (int n = 0; n < 2; ++n) _Pragma("unroll") for (int k = 0; k < 2; ++k) \
;         acc[ai][bj][m][n] = __builtin_amdgcn_mfma_f32_16x16x32_bf16(Bt[n][k], At[m][k], acc[ai][bj][m][n], 0, 0, 0); __builtin_amdgcn_s_setprio(0); } while (0)
; #define PG8_WAIT_V(n) asm volatile("s_waitcnt vmcnt(" #n ")" ::: "memory")
; #define PG8_WAIT_L(n) asm volatile("s_waitcnt lgkmcnt(" #n ")" ::: "memory")
; #define PG8_BAR __builtin_amdgcn_s_barrier()
; #define PG8_SCHED __builtin_amdgcn_sched_barrier(0)
; template <class Epi, class Sched, bool ALIGN_EPI = false, bool SP2 = false>
; __device__ __forceinline__ void gemm_phase(PG8_LAS unsigned char* lds, const Gemm g, const Sched& S, const Epi& E) {
;     ...
;         for (int t = 0; t < nt; t += 2) {
;             const bool last = (t == nt - 2);
;             const char* a1 = cA + (size_t)(t + 1) * kstep;
;             const char* a2 = last ? nA : cA + (size_t)(t + 2) * kstep; const char* b2 = last ? nB : cB + (size_t)(t + 2) * kstep;
;             const char* a3 = a2 + kstep; const char* b3 = b2 + kstep;
;             if (last && has_next) S.a_ready(nxt);
;             if constexpr (SP2) {
;             PG8_LDB(B0, 0, 0); PG8_LDB(B1, 0, 1); PG8_SCHED; PG8_LDA(At, 0, 0); PG8_STAGE(PG8_SA(1, 1), a1 + hstep, voffA);
;             PG8_WAIT_V(8); PG8_WAIT_L(0); PG8_BAR; PG8_MMA(0, 0, At, B0); PG8_MMA(0, 1, At, B1); PG8_BAR; PG8_SCHED;
;             PG8_LDA(At, 0, 1); PG8_STAGE(PG8_SB(0, 0), b2, voffB); PG8_STAGE(PG8_SB(0, 1), b2 + hstep, voffB); PG8_STAGE(PG8_SA(0, 0), a2, voffA);
.LBB0_622:
	s_add_u32 s6, s4, 0xfffc0080
	s_addc_u32 s7, s5, -1
	s_cmp_eq_u32 s35, 12
	s_cselect_b32 s9, s10, s7
	s_cselect_b32 s8, s11, s6
	s_cselect_b32 s7, s19, s34
	s_cselect_b32 s6, s23, s25
	s_add_i32 s36, 0, 0x10000
	v_add_u32_e32 v0, s36, v176
	s_add_i32 s38, 0, 0x14000
	ds_read_b128 v[58:61], v0
	ds_read_b128 v[62:65], v0 offset:1024
	ds_read_b128 v[66:69], v0 offset:2048
	ds_read_b128 v[70:73], v0 offset:3072
	v_add_u32_e32 v0, s38, v176
	ds_read_b128 v[74:77], v0
	ds_read_b128 v[78:81], v0 offset:1024
	ds_read_b128 v[82:85], v0 offset:2048
	ds_read_b128 v[172:175], v0 offset:3072
	v_lshl_add_u64 v[86:87], s[4:5], 0, v[168:169]
	s_add_i32 m0, s12, 0xc000
	ds_read_b128 v[178:181], v177
	ds_read_b128 v[182:185], v177 offset:1024
	ds_read_b128 v[186:189], v177 offset:2048
	ds_read_b128 v[190:193], v177 offset:3072
	ds_read_b128 v[194:197], v177 offset:4096
	ds_read_b128 v[198:201], v177 offset:5120
	ds_read_b128 v[206:209], v177 offset:6144
	ds_read_b128 v[210:213], v177 offset:7168
	global_load_lds_dwordx4 v[86:87], off
	v_lshl_add_u64 v[86:87], s[4:5], 0, v[170:171]
	s_add_i32 m0, s12, 0xe000
	s_nop 0
	global_load_lds_dwordx4 v[86:87], off
	s_waitcnt vmcnt(8)
	s_waitcnt lgkmcnt(0)
	s_barrier
	s_setprio 1
	s_waitcnt lgkmcnt(0)
	v_mfma_f32_16x16x32_bf16 v[156:159], v[58:61], v[178:181], v[156:159]
	v_mfma_f32_16x16x32_bf16 v[152:155], v[66:69], v[178:181], v[152:155]
	v_mfma_f32_16x16x32_bf16 v[140:143], v[58:61], v[186:189], v[140:143]
	v_mfma_f32_16x16x32_bf16 v[136:139], v[66:69], v[186:189], v[136:139]
	v_mfma_f32_16x16x32_bf16 v[124:127], v[58:61], v[194:197], v[124:127]
	v_mfma_f32_16x16x32_bf16 v[120:123], v[66:69], v[194:197], v[120:123]
	v_mfma_f32_16x16x32_bf16 v[108:111], v[58:61], v[206:209], v[108:111]
	v_mfma_f32_16x16x32_bf16 v[104:107], v[66:69], v[206:209], v[104:107]
	v_mfma_f32_16x16x32_bf16 v[156:159], v[62:65], v[182:185], v[156:159]
	v_mfma_f32_16x16x32_bf16 v[152:155], v[70:73], v[182:185], v[152:155]
	v_mfma_f32_16x16x32_bf16 v[140:143], v[62:65], v[190:193], v[140:143]
	v_mfma_f32_16x16x32_bf16 v[136:139], v[70:73], v[190:193], v[136:139]
	v_mfma_f32_16x16x32_bf16 v[124:127], v[62:65], v[198:201], v[124:127]
	v_mfma_f32_16x16x32_bf16 v[120:123], v[70:73], v[198:201], v[120:123]
	v_mfma_f32_16x16x32_bf16 v[108:111], v[62:65], v[210:213], v[108:111]
	v_mfma_f32_16x16x32_bf16 v[104:107], v[70:73], v[210:213], v[104:107]
	v_mfma_f32_16x16x32_bf16 v[148:151], v[74:77], v[178:181], v[148:151]
	v_mfma_f32_16x16x32_bf16 v[144:147], v[82:85], v[178:181], v[144:147]
	v_mfma_f32_16x16x32_bf16 v[132:135], v[74:77], v[186:189], v[132:135]
	v_mfma_f32_16x16x32_bf16 v[128:131], v[82:85], v[186:189], v[128:131]
	v_mfma_f32_16x16x32_bf16 v[116:119], v[74:77], v[194:197], v[116:119]
	v_mfma_f32_16x16x32_bf16 v[112:115], v[82:85], v[194:197], v[112:115]
	v_mfma_f32_16x16x32_bf16 v[100:103], v[74:77], v[206:209], v[100:103]
	v_mfma_f32_16x16x32_bf16 v[96:99], v[82:85], v[206:209], v[96:99]
	v_mfma_f32_16x16x32_bf16 v[148:151], v[78:81], v[182:185], v[148:151]
	v_mfma_f32_16x16x32_bf16 v[144:147], v[172:175], v[182:185], v[144:147]
	v_mfma_f32_16x16x32_bf16 v[132:135], v[78:81], v[190:193], v[132:135]
	v_mfma_f32_16x16x32_bf16 v[128:131], v[172:175], v[190:193], v[128:131]
	v_mfma_f32_16x16x32_bf16 v[116:119], v[78:81], v[198:201], v[116:119]
	v_mfma_f32_16x16x32_bf16 v[112:115], v[172:175], v[198:201], v[112:115]
	v_mfma_f32_16x16x32_bf16 v[100:103], v[78:81], v[210:213], v[100:103]
	v_mfma_f32_16x16x32_bf16 v[96:99], v[172:175], v[210:213], v[96:99]
	s_setprio 0
	s_barrier
	s_add_i32 s36, s36, s2
	v_lshl_add_u64 v[214:215], s[6:7], 0, v[164:165]
	s_mov_b32 m0, s36
	ds_read_b128 v[178:181], v177 offset:16384
	ds_read_b128 v[182:185], v177 offset:17408
	ds_read_b128 v[186:189], v177 offset:18432
	ds_read_b128 v[190:193], v177 offset:19456
	ds_read_b128 v[194:197], v177 offset:20480
	ds_read_b128 v[198:201], v177 offset:21504
	ds_read_b128 v[206:209], v177 offset:22528
	ds_read_b128 v[210:213], v177 offset:23552
	global_load_lds_dwordx4 v[214:215], off
	s_add_i32 m0, s36, 0x2000
	s_add_u32 s36, s6, 0x40000
	v_lshl_add_u64 v[216:217], s[6:7], 0, v[160:161]
	s_addc_u32 s37, s7, 0
	s_add_i32 s38, s38, s2
	global_load_lds_dwordx4 v[216:217], off
	v_lshl_add_u64 v[86:87], s[36:37], 0, v[164:165]
	s_mov_b32 m0, s38
	v_lshl_add_u64 v[218:219], s[8:9], 0, v[166:167]
	global_load_lds_dwordx4 v[86:87], off
	v_lshl_add_u64 v[86:87], s[36:37], 0, v[160:161]
	s_add_i32 m0, s38, 0x2000
	v_lshl_add_u64 v[220:221], s[8:9], 0, v[162:163]
	global_load_lds_dwordx4 v[86:87], off
	s_mov_b32 m0, s12
	s_nop 0
	global_load_lds_dwordx4 v[218:219], off
	s_mov_b32 m0, s13
	s_nop 0
	global_load_lds_dwordx4 v[220:221], off
	s_waitcnt vmcnt(8)
	s_waitcnt lgkmcnt(0)
	s_barrier
; #define PG8_STAGE(bufoff, gbase, voff) do { _Pragma("unroll") for (int _i = 0; _i < 2; ++_i) \
;         __builtin_amdgcn_global_load_lds((const unsigned*)((const char*)(gbase) + (voff)[_i]), (PG8_LAS unsigned*)(lds + (bufoff) + ldsw + _i * 8192), 16, 0, 0); } while (0)
; #define PG8_LDA(dst, b, h) do { _Pragma("unroll") for (int m = 0; m < 4; ++m) _Pragma("unroll") for (int k = 0; k < 2; ++k) dst[m][k] = *(const PG8_LAS bf16x8*)(lds + PG8_SA(b, h) + aoff + m * 2048 + k * 1024); } while (0)
; #define PG8_LDB(dst, b, h) do { _Pragma("unroll") for (int n = 0; n < 2; ++n) _Pragma("unroll") for (int k = 0; k < 2; ++k) dst[n][k] = *(const PG8_LAS bf16x8*)(lds + PG8_SB(b, h) + boff + n * 2048 + k * 1024); } while (0)
; #define PG8_MMA(ai, bj, At, Bt) do { __builtin_amdgcn_s_setprio(1); _Pragma("unroll") for (int m = 0; m < 4; ++m) _Pragma("unroll") for (int n = 0; n < 2; ++n) _Pragma("unroll") for (int k = 0; k < 2; ++k) \
;         acc[ai][bj][m][n] = __builtin_amdgcn_mfma_f32_16x16x32_bf16(Bt[n][k], At[m][k], acc[ai][bj][m][n], 0, 0, 0); __builtin_amdgcn_s_setprio(0); } while (0)
; #define PG8_WAIT_V(n) asm volatile("s_waitcnt vmcnt(" #n ")" ::: "memory")
; #define PG8_WAIT_L(n) asm volatile("s_waitcnt lgkmcnt(" #n ")" ::: "memory")
; #define PG8_BAR __builtin_amdgcn_s_barrier()
; #define PG8_SCHED __builtin_amdgcn_sched_barrier(0)
; template <class Epi, class Sched, bool ALIGN_EPI = false, bool SP2 = false>
; __device__ __forceinline__ void gemm_phase(PG8_LAS unsigned char* lds, const Gemm g, const Sched& S, const Epi& E) {
;     ...
;             PG8_WAIT_V(8); PG8_WAIT_L(0); PG8_BAR; PG8_MMA(1, 0, At, B0); PG8_MMA(1, 1, At, B1); PG8_BAR; PG8_SCHED;
;             PG8_LDB(B0, 1, 0); PG8_LDB(B1, 1, 1); PG8_SCHED; PG8_LDA(At, 1, 0); PG8_STAGE(PG8_SA(0, 1), a2 + hstep, voffA);
;             PG8_WAIT_V(8); PG8_WAIT_L(0); PG8_BAR; PG8_MMA(0, 0, At, B0); PG8_MMA(0, 1, At, B1); PG8_BAR; PG8_SCHED;
	s_setprio 1
	s_waitcnt lgkmcnt(0)
	v_mfma_f32_16x16x32_bf16 v[92:95], v[58:61], v[178:181], v[92:95]
	v_mfma_f32_16x16x32_bf16 v[86:89], v[66:69], v[178:181], v[88:91]
	v_mfma_f32_16x16x32_bf16 v[46:49], v[58:61], v[186:189], v[46:49]
	v_mfma_f32_16x16x32_bf16 v[42:45], v[66:69], v[186:189], v[42:45]
	v_mfma_f32_16x16x32_bf16 v[30:33], v[58:61], v[194:197], v[30:33]
	v_mfma_f32_16x16x32_bf16 v[26:29], v[66:69], v[194:197], v[26:29]
	v_mfma_f32_16x16x32_bf16 v[14:17], v[58:61], v[206:209], v[14:17]
	v_mfma_f32_16x16x32_bf16 v[10:13], v[66:69], v[206:209], v[10:13]
	v_mfma_f32_16x16x32_bf16 v[92:95], v[62:65], v[182:185], v[92:95]
	v_mfma_f32_16x16x32_bf16 v[86:89], v[70:73], v[182:185], v[86:89]
	v_mfma_f32_16x16x32_bf16 v[46:49], v[62:65], v[190:193], v[46:49]
	v_mfma_f32_16x16x32_bf16 v[42:45], v[70:73], v[190:193], v[42:45]
	v_mfma_f32_16x16x32_bf16 v[30:33], v[62:65], v[198:201], v[30:33]
	v_mfma_f32_16x16x32_bf16 v[26:29], v[70:73], v[198:201], v[26:29]
	v_mfma_f32_16x16x32_bf16 v[14:17], v[62:65], v[210:213], v[14:17]
	v_mfma_f32_16x16x32_bf16 v[10:13], v[70:73], v[210:213], v[10:13]
	v_mfma_f32_16x16x32_bf16 v[54:57], v[74:77], v[178:181], v[54:57]
	v_mfma_f32_16x16x32_bf16 v[50:53], v[82:85], v[178:181], v[50:53]
	v_mfma_f32_16x16x32_bf16 v[38:41], v[74:77], v[186:189], v[38:41]
	v_mfma_f32_16x16x32_bf16 v[34:37], v[82:85], v[186:189], v[34:37]
	v_mfma_f32_16x16x32_bf16 v[22:25], v[74:77], v[194:197], v[22:25]
	v_mfma_f32_16x16x32_bf16 v[18:21], v[82:85], v[194:197], v[18:21]
	v_mfma_f32_16x16x32_bf16 v[6:9], v[74:77], v[206:209], v[6:9]
	v_mfma_f32_16x16x32_bf16 v[2:5], v[82:85], v[206:209], v[2:5]
	v_mfma_f32_16x16x32_bf16 v[54:57], v[78:81], v[182:185], v[54:57]
	v_mfma_f32_16x16x32_bf16 v[50:53], v[172:175], v[182:185], v[50:53]
	v_mfma_f32_16x16x32_bf16 v[38:41], v[78:81], v[190:193], v[38:41]
	v_mfma_f32_16x16x32_bf16 v[34:37], v[172:175], v[190:193], v[34:37]
	v_mfma_f32_16x16x32_bf16 v[22:25], v[78:81], v[198:201], v[22:25]
	v_mfma_f32_16x16x32_bf16 v[18:21], v[172:175], v[198:201], v[18:21]
	v_mfma_f32_16x16x32_bf16 v[6:9], v[78:81], v[210:213], v[6:9]
	v_mfma_f32_16x16x32_bf16 v[2:5], v[172:175], v[210:213], v[2:5]
	s_setprio 0
	s_barrier
	s_add_i32 s36, 0, 0x18000
	v_add_u32_e32 v0, s36, v176
	s_add_i32 s37, 0, 0x1c000
	ds_read_b128 v[58:61], v0
	ds_read_b128 v[62:65], v0 offset:1024
	ds_read_b128 v[66:69], v0 offset:2048
	ds_read_b128 v[70:73], v0 offset:3072
	v_add_u32_e32 v0, s37, v176
	ds_read_b128 v[74:77], v0
	ds_read_b128 v[78:81], v0 offset:1024
	ds_read_b128 v[82:85], v0 offset:2048
	ds_read_b128 v[172:175], v0 offset:3072
	s_add_u32 s8, s8, 0x40000
	s_addc_u32 s9, s9, 0
	s_mov_b32 m0, s14
	v_lshl_add_u64 v[90:91], s[8:9], 0, v[166:167]
	ds_read_b128 v[178:181], v177 offset:32768
	ds_read_b128 v[182:185], v177 offset:33792
	ds_read_b128 v[186:189], v177 offset:34816
	ds_read_b128 v[190:193], v177 offset:35840
	ds_read_b128 v[194:197], v177 offset:36864
	ds_read_b128 v[198:201], v177 offset:37888
	ds_read_b128 v[206:209], v177 offset:38912
	ds_read_b128 v[210:213], v177 offset:39936
	global_load_lds_dwordx4 v[90:91], off
	v_lshl_add_u64 v[90:91], s[8:9], 0, v[162:163]
	s_mov_b32 m0, s15
	s_nop 0
	global_load_lds_dwordx4 v[90:91], off
	s_waitcnt vmcnt(8)
	s_waitcnt lgkmcnt(0)
	s_barrier
	s_setprio 1
	s_waitcnt lgkmcnt(0)
	v_mfma_f32_16x16x32_bf16 v[156:159], v[58:61], v[178:181], v[156:159]
	v_mfma_f32_16x16x32_bf16 v[152:155], v[66:69], v[178:181], v[152:155]
	v_mfma_f32_16x16x32_bf16 v[140:143], v[58:61], v[186:189], v[140:143]
	v_mfma_f32_16x16x32_bf16 v[136:139], v[66:69], v[186:189], v[136:139]
	v_mfma_f32_16x16x32_bf16 v[124:127], v[58:61], v[194:197], v[124:127]
	v_mfma_f32_16x16x32_bf16 v[120:123], v[66:69], v[194:197], v[120:123]
	v_mfma_f32_16x16x32_bf16 v[108:111], v[58:61], v[206:209], v[108:111]
	v_mfma_f32_16x16x32_bf16 v[104:107], v[66:69], v[206:209], v[104:107]
	v_mfma_f32_16x16x32_bf16 v[156:159], v[62:65], v[182:185], v[156:159]
	v_mfma_f32_16x16x32_bf16 v[152:155], v[70:73], v[182:185], v[152:155]
	v_mfma_f32_16x16x32_bf16 v[140:143], v[62:65], v[190:193], v[140:143]
	v_mfma_f32_16x16x32_bf16 v[136:139], v[70:73], v[190:193], v[136:139]
	v_mfma_f32_16x16x32_bf16 v[124:127], v[62:65], v[198:201], v[124:127]
	v_mfma_f32_16x16x32_bf16 v[120:123], v[70:73], v[198:201], v[120:123]
	v_mfma_f32_16x16x32_bf16 v[108:111], v[62:65], v[210:213], v[108:111]
	v_mfma_f32_16x16x32_bf16 v[104:107], v[70:73], v[210:213], v[104:107]
	v_mfma_f32_16x16x32_bf16 v[148:151], v[74:77], v[178:181], v[148:151]
	v_mfma_f32_16x16x32_bf16 v[144:147], v[82:85], v[178:181], v[144:147]
	v_mfma_f32_16x16x32_bf16 v[132:135], v[74:77], v[186:189], v[132:135]
	v_mfma_f32_16x16x32_bf16 v[128:131], v[82:85], v[186:189], v[128:131]
	v_mfma_f32_16x16x32_bf16 v[116:119], v[74:77], v[194:197], v[116:119]
	v_mfma_f32_16x16x32_bf16 v[112:115], v[82:85], v[194:197], v[112:115]
	v_mfma_f32_16x16x32_bf16 v[100:103], v[74:77], v[206:209], v[100:103]
	v_mfma_f32_16x16x32_bf16 v[96:99], v[82:85], v[206:209], v[96:99]
	v_mfma_f32_16x16x32_bf16 v[148:151], v[78:81], v[182:185], v[148:151]
	v_mfma_f32_16x16x32_bf16 v[144:147], v[172:175], v[182:185], v[144:147]
	v_mfma_f32_16x16x32_bf16 v[132:135], v[78:81], v[190:193], v[132:135]
	v_mfma_f32_16x16x32_bf16 v[128:131], v[172:175], v[190:193], v[128:131]
	v_mfma_f32_16x16x32_bf16 v[116:119], v[78:81], v[198:201], v[116:119]
	v_mfma_f32_16x16x32_bf16 v[112:115], v[172:175], v[198:201], v[112:115]
	v_mfma_f32_16x16x32_bf16 v[100:103], v[78:81], v[210:213], v[100:103]
	v_mfma_f32_16x16x32_bf16 v[96:99], v[172:175], v[210:213], v[96:99]
	s_setprio 0
	s_barrier
; #define PG8_STAGE(bufoff, gbase, voff) do { _Pragma("unroll") for (int _i = 0; _i < 2; ++_i) \
;         __builtin_amdgcn_global_load_lds((const unsigned*)((const char*)(gbase) + (voff)[_i]), (PG8_LAS unsigned*)(lds + (bufoff) + ldsw + _i * 8192), 16, 0, 0); } while (0)
; #define PG8_LDA(dst, b, h) do { _Pragma("unroll") for (int m = 0; m < 4; ++m) _Pragma("unroll") for (int k = 0; k < 2; ++k) dst[m][k] = *(const PG8_LAS bf16x8*)(lds + PG8_SA(b, h) + aoff + m * 2048 + k * 1024); } while (0)
; #define PG8_MMA(ai, bj, At, Bt) do { __builtin_amdgcn_s_setprio(1); _Pragma("unroll") for (int m = 0; m < 4; ++m) _Pragma("unroll") for (int n = 0; n < 2; ++n) _Pragma("unroll") for (int k = 0; k < 2; ++k) \
;         acc[ai][bj][m][n] = __builtin_amdgcn_mfma_f32_16x16x32_bf16(Bt[n][k], At[m][k], acc[ai][bj][m][n], 0, 0, 0); __builtin_amdgcn_s_setprio(0); } while (0)
; #define PG8_WAIT_V(n) asm volatile("s_waitcnt vmcnt(" #n ")" ::: "memory")
; #define PG8_WAIT_L(n) asm volatile("s_waitcnt lgkmcnt(" #n ")" ::: "memory")
; #define PG8_BAR __builtin_amdgcn_s_barrier()
; #define PG8_SCHED __builtin_amdgcn_sched_barrier(0)
; template <class Epi, class Sched, bool ALIGN_EPI = false, bool SP2 = false>
; __device__ __forceinline__ void gemm_phase(PG8_LAS unsigned char* lds, const Gemm g, const Sched& S, const Epi& E) {
;     ...
;             PG8_LDA(At, 1, 1); PG8_STAGE(PG8_SB(1, 0), b3, voffB); PG8_STAGE(PG8_SB(1, 1), b3 + hstep, voffB); PG8_STAGE(PG8_SA(1, 0), a3, voffA);
;             PG8_WAIT_V(8); PG8_WAIT_L(0); PG8_BAR; PG8_MMA(1, 0, At, B0); PG8_MMA(1, 1, At, B1); PG8_BAR; PG8_SCHED;
;     ...
;         if constexpr (ALIGN_EPI) { if (wr == 0) PG8_BAR; }
	s_add_i32 s8, s36, s2
	v_lshl_add_u64 v[90:91], v[214:215], 0, s[40:41]
	s_mov_b32 m0, s8
	ds_read_b128 v[178:181], v177 offset:49152
	ds_read_b128 v[182:185], v177 offset:50176
	ds_read_b128 v[186:189], v177 offset:51200
	ds_read_b128 v[190:193], v177 offset:52224
	ds_read_b128 v[194:197], v177 offset:53248
	ds_read_b128 v[198:201], v177 offset:54272
	ds_read_b128 v[206:209], v177 offset:55296
	ds_read_b128 v[210:213], v177 offset:56320
	global_load_lds_dwordx4 v[90:91], off
	s_add_i32 m0, s8, 0x2000
	s_add_u32 s6, s6, 0x40080
	v_lshl_add_u64 v[90:91], v[216:217], 0, s[40:41]
	s_addc_u32 s7, s7, 0
	s_add_i32 s8, s37, s2
	global_load_lds_dwordx4 v[90:91], off
	v_lshl_add_u64 v[90:91], s[6:7], 0, v[164:165]
	s_mov_b32 m0, s8
	s_nop 0
	global_load_lds_dwordx4 v[90:91], off
	v_lshl_add_u64 v[90:91], s[6:7], 0, v[160:161]
	s_add_i32 m0, s8, 0x2000
	s_nop 0
	global_load_lds_dwordx4 v[90:91], off
	v_lshl_add_u64 v[90:91], v[218:219], 0, s[40:41]
	s_mov_b32 m0, s16
	s_nop 0
	global_load_lds_dwordx4 v[90:91], off
	v_lshl_add_u64 v[90:91], v[220:221], 0, s[40:41]
	s_mov_b32 m0, s17
	s_nop 0
	global_load_lds_dwordx4 v[90:91], off
	s_waitcnt vmcnt(8)
	s_waitcnt lgkmcnt(0)
	s_barrier
	s_setprio 1
	s_waitcnt lgkmcnt(0)
	v_mfma_f32_16x16x32_bf16 v[90:93], v[58:61], v[178:181], v[92:95]
	v_mfma_f32_16x16x32_bf16 v[86:89], v[66:69], v[178:181], v[86:89]
	v_mfma_f32_16x16x32_bf16 v[46:49], v[58:61], v[186:189], v[46:49]
	v_mfma_f32_16x16x32_bf16 v[42:45], v[66:69], v[186:189], v[42:45]
	v_mfma_f32_16x16x32_bf16 v[30:33], v[58:61], v[194:197], v[30:33]
	v_mfma_f32_16x16x32_bf16 v[26:29], v[66:69], v[194:197], v[26:29]
	v_mfma_f32_16x16x32_bf16 v[14:17], v[58:61], v[206:209], v[14:17]
	v_mfma_f32_16x16x32_bf16 v[10:13], v[66:69], v[206:209], v[10:13]
	v_mfma_f32_16x16x32_bf16 v[92:95], v[62:65], v[182:185], v[90:93]
	v_mfma_f32_16x16x32_bf16 v[88:91], v[70:73], v[182:185], v[86:89]
	v_mfma_f32_16x16x32_bf16 v[46:49], v[62:65], v[190:193], v[46:49]
	v_mfma_f32_16x16x32_bf16 v[42:45], v[70:73], v[190:193], v[42:45]
	v_mfma_f32_16x16x32_bf16 v[30:33], v[62:65], v[198:201], v[30:33]
	v_mfma_f32_16x16x32_bf16 v[26:29], v[70:73], v[198:201], v[26:29]
	v_mfma_f32_16x16x32_bf16 v[14:17], v[62:65], v[210:213], v[14:17]
	v_mfma_f32_16x16x32_bf16 v[10:13], v[70:73], v[210:213], v[10:13]
	v_mfma_f32_16x16x32_bf16 v[54:57], v[74:77], v[178:181], v[54:57]
	v_mfma_f32_16x16x32_bf16 v[50:53], v[82:85], v[178:181], v[50:53]
	v_mfma_f32_16x16x32_bf16 v[38:41], v[74:77], v[186:189], v[38:41]
	v_mfma_f32_16x16x32_bf16 v[34:37], v[82:85], v[186:189], v[34:37]
	v_mfma_f32_16x16x32_bf16 v[22:25], v[74:77], v[194:197], v[22:25]
	v_mfma_f32_16x16x32_bf16 v[18:21], v[82:85], v[194:197], v[18:21]
	v_mfma_f32_16x16x32_bf16 v[6:9], v[74:77], v[206:209], v[6:9]
	v_mfma_f32_16x16x32_bf16 v[2:5], v[82:85], v[206:209], v[2:5]
	v_mfma_f32_16x16x32_bf16 v[54:57], v[78:81], v[182:185], v[54:57]
	v_mfma_f32_16x16x32_bf16 v[50:53], v[172:175], v[182:185], v[50:53]
	v_mfma_f32_16x16x32_bf16 v[38:41], v[78:81], v[190:193], v[38:41]
	v_mfma_f32_16x16x32_bf16 v[34:37], v[172:175], v[190:193], v[34:37]
	v_mfma_f32_16x16x32_bf16 v[22:25], v[78:81], v[198:201], v[22:25]
	v_mfma_f32_16x16x32_bf16 v[18:21], v[172:175], v[198:201], v[18:21]
	v_mfma_f32_16x16x32_bf16 v[6:9], v[78:81], v[210:213], v[6:9]
	v_mfma_f32_16x16x32_bf16 v[2:5], v[172:175], v[210:213], v[2:5]
	s_setprio 0
	s_barrier
	s_add_i32 s35, s35, 2
	s_add_u32 s4, s4, 0x100
	s_addc_u32 s5, s5, 0
	s_add_u32 s25, s25, 0x100
	s_addc_u32 s34, s34, 0
	s_cmp_gt_u32 s35, 13
	s_cbranch_scc0 .LBB0_622
	s_and_b64 vcc, exec, s[20:21]
	s_cbranch_vccz .LBB0_625
	s_barrier

; #define PG8_STAGE(bufoff, gbase, voff) do { _Pragma("unroll") for (int _i = 0; _i < 2; ++_i) \
;         __builtin_amdgcn_global_load_lds((const unsigned*)((const char*)(gbase) + (voff)[_i]), (PG8_LAS unsigned*)(lds + (bufoff) + ldsw + _i * 8192), 16, 0, 0); } while (0)
; #define PG8_LDA(dst, b, h) do { _Pragma("unroll") for (int m = 0; m < 4; ++m) _Pragma("unroll") for (int k = 0; k < 2; ++k) dst[m][k] = *(const PG8_LAS bf16x8*)(lds + PG8_SA(b, h) + aoff + m * 2048 + k * 1024); } while (0)
; #define PG8_LDB(dst, b, h) do { _Pragma("unroll") for (int n = 0; n < 2; ++n) _Pragma("unroll") for (int k = 0; k < 2; ++k) dst[n][k] = *(const PG8_LAS bf16x8*)(lds + PG8_SB(b, h) + boff + n * 2048 + k * 1024); } while (0)
; #define PG8_MMA(ai, bj, At, Bt) do { __builtin_amdgcn_s_setprio(1); _Pragma("unroll") for (int m = 0; m < 4; ++m) _Pragma("unroll") for (int n = 0; n < 2; ++n) _Pragma("unroll") for (int k = 0; k < 2; ++k) \
;         acc[ai][bj][m][n] = __builtin_amdgcn_mfma_f32_16x16x32_bf16(Bt[n][k], At[m][k], acc[ai][bj][m][n], 0, 0, 0); __builtin_amdgcn_s_setprio(0); } while (0)
; #define PG8_WAIT_V(n) asm volatile("s_waitcnt vmcnt(" #n ")" ::: "memory")
; #define PG8_WAIT_L(n) asm volatile("s_waitcnt lgkmcnt(" #n ")" ::: "memory")
; #define PG8_BAR __builtin_amdgcn_s_barrier()
; #define PG8_SCHED __builtin_amdgcn_sched_barrier(0)
; template <class Epi, class Sched, bool ALIGN_EPI = false, bool SP2 = false>
; __device__ __forceinline__ void gemm_phase(PG8_LAS unsigned char* lds, const Gemm g, const Sched& S, const Epi& E) {
;     ...
;         for (int t = 0; t < nt; t += 2) {
;             const bool last = (t == nt - 2);
;             const char* a1 = cA + (size_t)(t + 1) * kstep;
;             const char* a2 = last ? nA : cA + (size_t)(t + 2) * kstep; const char* b2 = last ? nB : cB + (size_t)(t + 2) * kstep;
;             const char* a3 = a2 + kstep; const char* b3 = b2 + kstep;
;             if (last && has_next) S.a_ready(nxt);
;             if constexpr (SP2) {
;             PG8_LDB(B0, 0, 0); PG8_LDB(B1, 0, 1); PG8_SCHED; PG8_LDA(At, 0, 0); PG8_STAGE(PG8_SA(1, 1), a1 + hstep, voffA);
;             PG8_WAIT_V(8); PG8_WAIT_L(0); PG8_BAR; PG8_MMA(0, 0, At, B0); PG8_MMA(0, 1, At, B1); PG8_BAR; PG8_SCHED;
;             PG8_LDA(At, 0, 1); PG8_STAGE(PG8_SB(0, 0), b2, voffB); PG8_STAGE(PG8_SB(0, 1), b2 + hstep, voffB); PG8_STAGE(PG8_SA(0, 0), a2, voffA);
.LBB0_739:
	s_add_u32 s6, s4, 0xfffc0080
	s_addc_u32 s7, s5, -1
	s_cmp_eq_u32 s35, 12
	s_cselect_b32 s9, s11, s7
	s_cselect_b32 s8, s19, s6
	s_cselect_b32 s7, s23, s34
	s_cselect_b32 s6, s25, s31
	s_add_i32 s36, 0, 0x10000
	v_add_u32_e32 v0, s36, v176
	s_add_i32 s38, 0, 0x14000
	ds_read_b128 v[58:61], v0
	ds_read_b128 v[62:65], v0 offset:1024
	ds_read_b128 v[66:69], v0 offset:2048
	ds_read_b128 v[70:73], v0 offset:3072
	v_add_u32_e32 v0, s38, v176
	ds_read_b128 v[74:77], v0
	ds_read_b128 v[78:81], v0 offset:1024
	ds_read_b128 v[82:85], v0 offset:2048
	ds_read_b128 v[172:175], v0 offset:3072
	v_lshl_add_u64 v[86:87], s[4:5], 0, v[168:169]
	s_add_i32 m0, s12, 0xc000
	ds_read_b128 v[178:181], v177
	ds_read_b128 v[182:185], v177 offset:1024
	ds_read_b128 v[186:189], v177 offset:2048
	ds_read_b128 v[190:193], v177 offset:3072
	ds_read_b128 v[194:197], v177 offset:4096
	ds_read_b128 v[198:201], v177 offset:5120
	ds_read_b128 v[206:209], v177 offset:6144
	ds_read_b128 v[210:213], v177 offset:7168
	global_load_lds_dwordx4 v[86:87], off
	v_lshl_add_u64 v[86:87], s[4:5], 0, v[170:171]
	s_add_i32 m0, s12, 0xe000
	s_nop 0
	global_load_lds_dwordx4 v[86:87], off
	s_waitcnt vmcnt(8)
	s_waitcnt lgkmcnt(0)
	s_barrier
	s_setprio 1
	s_waitcnt lgkmcnt(0)
	v_mfma_f32_16x16x32_bf16 v[156:159], v[58:61], v[178:181], v[156:159]
	v_mfma_f32_16x16x32_bf16 v[152:155], v[66:69], v[178:181], v[152:155]
	v_mfma_f32_16x16x32_bf16 v[140:143], v[58:61], v[186:189], v[140:143]
	v_mfma_f32_16x16x32_bf16 v[136:139], v[66:69], v[186:189], v[136:139]
	v_mfma_f32_16x16x32_bf16 v[124:127], v[58:61], v[194:197], v[124:127]
	v_mfma_f32_16x16x32_bf16 v[120:123], v[66:69], v[194:197], v[120:123]
	v_mfma_f32_16x16x32_bf16 v[108:111], v[58:61], v[206:209], v[108:111]
	v_mfma_f32_16x16x32_bf16 v[104:107], v[66:69], v[206:209], v[104:107]
	v_mfma_f32_16x16x32_bf16 v[156:159], v[62:65], v[182:185], v[156:159]
	v_mfma_f32_16x16x32_bf16 v[152:155], v[70:73], v[182:185], v[152:155]
	v_mfma_f32_16x16x32_bf16 v[140:143], v[62:65], v[190:193], v[140:143]
	v_mfma_f32_16x16x32_bf16 v[136:139], v[70:73], v[190:193], v[136:139]
	v_mfma_f32_16x16x32_bf16 v[124:127], v[62:65], v[198:201], v[124:127]
	v_mfma_f32_16x16x32_bf16 v[120:123], v[70:73], v[198:201], v[120:123]
	v_mfma_f32_16x16x32_bf16 v[108:111], v[62:65], v[210:213], v[108:111]
	v_mfma_f32_16x16x32_bf16 v[104:107], v[70:73], v[210:213], v[104:107]
	v_mfma_f32_16x16x32_bf16 v[148:151], v[74:77], v[178:181], v[148:151]
	v_mfma_f32_16x16x32_bf16 v[144:147], v[82:85], v[178:181], v[144:147]
	v_mfma_f32_16x16x32_bf16 v[132:135], v[74:77], v[186:189], v[132:135]
	v_mfma_f32_16x16x32_bf16 v[128:131], v[82:85], v[186:189], v[128:131]
	v_mfma_f32_16x16x32_bf16 v[116:119], v[74:77], v[194:197], v[116:119]
	v_mfma_f32_16x16x32_bf16 v[112:115], v[82:85], v[194:197], v[112:115]
	v_mfma_f32_16x16x32_bf16 v[100:103], v[74:77], v[206:209], v[100:103]
	v_mfma_f32_16x16x32_bf16 v[96:99], v[82:85], v[206:209], v[96:99]
	v_mfma_f32_16x16x32_bf16 v[148:151], v[78:81], v[182:185], v[148:151]
	v_mfma_f32_16x16x32_bf16 v[144:147], v[172:175], v[182:185], v[144:147]
	v_mfma_f32_16x16x32_bf16 v[132:135], v[78:81], v[190:193], v[132:135]
	v_mfma_f32_16x16x32_bf16 v[128:131], v[172:175], v[190:193], v[128:131]
	v_mfma_f32_16x16x32_bf16 v[116:119], v[78:81], v[198:201], v[116:119]
	v_mfma_f32_16x16x32_bf16 v[112:115], v[172:175], v[198:201], v[112:115]
	v_mfma_f32_16x16x32_bf16 v[100:103], v[78:81], v[210:213], v[100:103]
	v_mfma_f32_16x16x32_bf16 v[96:99], v[172:175], v[210:213], v[96:99]
	s_setprio 0
	s_barrier
	s_add_i32 s36, s36, s2
	v_lshl_add_u64 v[214:215], s[6:7], 0, v[164:165]
	s_mov_b32 m0, s36
	ds_read_b128 v[178:181], v177 offset:16384
	ds_read_b128 v[182:185], v177 offset:17408
	ds_read_b128 v[186:189], v177 offset:18432
	ds_read_b128 v[190:193], v177 offset:19456
	ds_read_b128 v[194:197], v177 offset:20480
	ds_read_b128 v[198:201], v177 offset:21504
	ds_read_b128 v[206:209], v177 offset:22528
	ds_read_b128 v[210:213], v177 offset:23552
	global_load_lds_dwordx4 v[214:215], off
	s_add_i32 m0, s36, 0x2000
	s_add_u32 s36, s6, 0x40000
	v_lshl_add_u64 v[216:217], s[6:7], 0, v[160:161]
	s_addc_u32 s37, s7, 0
	s_add_i32 s38, s38, s2
	global_load_lds_dwordx4 v[216:217], off
	v_lshl_add_u64 v[86:87], s[36:37], 0, v[164:165]
	s_mov_b32 m0, s38
	v_lshl_add_u64 v[218:219], s[8:9], 0, v[166:167]
	global_load_lds_dwordx4 v[86:87], off
	v_lshl_add_u64 v[86:87], s[36:37], 0, v[160:161]
	s_add_i32 m0, s38, 0x2000
	v_lshl_add_u64 v[220:221], s[8:9], 0, v[162:163]
	global_load_lds_dwordx4 v[86:87], off
	s_mov_b32 m0, s12
	s_nop 0
	global_load_lds_dwordx4 v[218:219], off
	s_mov_b32 m0, s13
	s_nop 0
	global_load_lds_dwordx4 v[220:221], off
	s_waitcnt vmcnt(8)
	s_waitcnt lgkmcnt(0)
	s_barrier
; #define PG8_STAGE(bufoff, gbase, voff) do { _Pragma("unroll") for (int _i = 0; _i < 2; ++_i) \
;         __builtin_amdgcn_global_load_lds((const unsigned*)((const char*)(gbase) + (voff)[_i]), (PG8_LAS unsigned*)(lds + (bufoff) + ldsw + _i * 8192), 16, 0, 0); } while (0)
; #define PG8_LDA(dst, b, h) do { _Pragma("unroll") for (int m = 0; m < 4; ++m) _Pragma("unroll") for (int k = 0; k < 2; ++k) dst[m][k] = *(const PG8_LAS bf16x8*)(lds + PG8_SA(b, h) + aoff + m * 2048 + k * 1024); } while (0)
; #define PG8_LDB(dst, b, h) do { _Pragma("unroll") for (int n = 0; n < 2; ++n) _Pragma("unroll") for (int k = 0; k < 2; ++k) dst[n][k] = *(const PG8_LAS bf16x8*)(lds + PG8_SB(b, h) + boff + n * 2048 + k * 1024); } while (0)
; #define PG8_MMA(ai, bj, At, Bt) do { __builtin_amdgcn_s_setprio(1); _Pragma("unroll") for (int m = 0; m < 4; ++m) _Pragma("unroll") for (int n = 0; n < 2; ++n) _Pragma("unroll") for (int k = 0; k < 2; ++k) \
;         acc[ai][bj][m][n] = __builtin_amdgcn_mfma_f32_16x16x32_bf16(Bt[n][k], At[m][k], acc[ai][bj][m][n], 0, 0, 0); __builtin_amdgcn_s_setprio(0); } while (0)
; #define PG8_WAIT_V(n) asm volatile("s_waitcnt vmcnt(" #n ")" ::: "memory")
; #define PG8_WAIT_L(n) asm volatile("s_waitcnt lgkmcnt(" #n ")" ::: "memory")
; #define PG8_BAR __builtin_amdgcn_s_barrier()
; #define PG8_SCHED __builtin_amdgcn_sched_barrier(0)
; template <class Epi, class Sched, bool ALIGN_EPI = false, bool SP2 = false>
; __device__ __forceinline__ void gemm_phase(PG8_LAS unsigned char* lds, const Gemm g, const Sched& S, const Epi& E) {
;     ...
;             PG8_WAIT_V(8); PG8_WAIT_L(0); PG8_BAR; PG8_MMA(1, 0, At, B0); PG8_MMA(1, 1, At, B1); PG8_BAR; PG8_SCHED;
;             PG8_LDB(B0, 1, 0); PG8_LDB(B1, 1, 1); PG8_SCHED; PG8_LDA(At, 1, 0); PG8_STAGE(PG8_SA(0, 1), a2 + hstep, voffA);
;             PG8_WAIT_V(8); PG8_WAIT_L(0); PG8_BAR; PG8_MMA(0, 0, At, B0); PG8_MMA(0, 1, At, B1); PG8_BAR; PG8_SCHED;
	s_setprio 1
	s_waitcnt lgkmcnt(0)
	v_mfma_f32_16x16x32_bf16 v[92:95], v[58:61], v[178:181], v[92:95]
	v_mfma_f32_16x16x32_bf16 v[86:89], v[66:69], v[178:181], v[88:91]
	v_mfma_f32_16x16x32_bf16 v[46:49], v[58:61], v[186:189], v[46:49]
	v_mfma_f32_16x16x32_bf16 v[42:45], v[66:69], v[186:189], v[42:45]
	v_mfma_f32_16x16x32_bf16 v[30:33], v[58:61], v[194:197], v[30:33]
	v_mfma_f32_16x16x32_bf16 v[26:29], v[66:69], v[194:197], v[26:29]
	v_mfma_f32_16x16x32_bf16 v[14:17], v[58:61], v[206:209], v[14:17]
	v_mfma_f32_16x16x32_bf16 v[10:13], v[66:69], v[206:209], v[10:13]
	v_mfma_f32_16x16x32_bf16 v[92:95], v[62:65], v[182:185], v[92:95]
	v_mfma_f32_16x16x32_bf16 v[86:89], v[70:73], v[182:185], v[86:89]
	v_mfma_f32_16x16x32_bf16 v[46:49], v[62:65], v[190:193], v[46:49]
	v_mfma_f32_16x16x32_bf16 v[42:45], v[70:73], v[190:193], v[42:45]
	v_mfma_f32_16x16x32_bf16 v[30:33], v[62:65], v[198:201], v[30:33]
	v_mfma_f32_16x16x32_bf16 v[26:29], v[70:73], v[198:201], v[26:29]
	v_mfma_f32_16x16x32_bf16 v[14:17], v[62:65], v[210:213], v[14:17]
	v_mfma_f32_16x16x32_bf16 v[10:13], v[70:73], v[210:213], v[10:13]
	v_mfma_f32_16x16x32_bf16 v[54:57], v[74:77], v[178:181], v[54:57]
	v_mfma_f32_16x16x32_bf16 v[50:53], v[82:85], v[178:181], v[50:53]
	v_mfma_f32_16x16x32_bf16 v[38:41], v[74:77], v[186:189], v[38:41]
	v_mfma_f32_16x16x32_bf16 v[34:37], v[82:85], v[186:189], v[34:37]
	v_mfma_f32_16x16x32_bf16 v[22:25], v[74:77], v[194:197], v[22:25]
	v_mfma_f32_16x16x32_bf16 v[18:21], v[82:85], v[194:197], v[18:21]
	v_mfma_f32_16x16x32_bf16 v[6:9], v[74:77], v[206:209], v[6:9]
	v_mfma_f32_16x16x32_bf16 v[2:5], v[82:85], v[206:209], v[2:5]
	v_mfma_f32_16x16x32_bf16 v[54:57], v[78:81], v[182:185], v[54:57]
	v_mfma_f32_16x16x32_bf16 v[50:53], v[172:175], v[182:185], v[50:53]
	v_mfma_f32_16x16x32_bf16 v[38:41], v[78:81], v[190:193], v[38:41]
	v_mfma_f32_16x16x32_bf16 v[34:37], v[172:175], v[190:193], v[34:37]
	v_mfma_f32_16x16x32_bf16 v[22:25], v[78:81], v[198:201], v[22:25]
	v_mfma_f32_16x16x32_bf16 v[18:21], v[172:175], v[198:201], v[18:21]
	v_mfma_f32_16x16x32_bf16 v[6:9], v[78:81], v[210:213], v[6:9]
	v_mfma_f32_16x16x32_bf16 v[2:5], v[172:175], v[210:213], v[2:5]
	s_setprio 0
	s_barrier
	s_add_i32 s36, 0, 0x18000
	v_add_u32_e32 v0, s36, v176
	s_add_i32 s37, 0, 0x1c000
	ds_read_b128 v[58:61], v0
	ds_read_b128 v[62:65], v0 offset:1024
	ds_read_b128 v[66:69], v0 offset:2048
	ds_read_b128 v[70:73], v0 offset:3072
	v_add_u32_e32 v0, s37, v176
	ds_read_b128 v[74:77], v0
	ds_read_b128 v[78:81], v0 offset:1024
	ds_read_b128 v[82:85], v0 offset:2048
	ds_read_b128 v[172:175], v0 offset:3072
	s_add_u32 s8, s8, 0x40000
	s_addc_u32 s9, s9, 0
	s_mov_b32 m0, s14
	v_lshl_add_u64 v[90:91], s[8:9], 0, v[166:167]
	ds_read_b128 v[178:181], v177 offset:32768
	ds_read_b128 v[182:185], v177 offset:33792
	ds_read_b128 v[186:189], v177 offset:34816
	ds_read_b128 v[190:193], v177 offset:35840
	ds_read_b128 v[194:197], v177 offset:36864
	ds_read_b128 v[198:201], v177 offset:37888
	ds_read_b128 v[206:209], v177 offset:38912
	ds_read_b128 v[210:213], v177 offset:39936
	global_load_lds_dwordx4 v[90:91], off
	v_lshl_add_u64 v[90:91], s[8:9], 0, v[162:163]
	s_mov_b32 m0, s15
	s_nop 0
	global_load_lds_dwordx4 v[90:91], off
	s_waitcnt vmcnt(8)
	s_waitcnt lgkmcnt(0)
	s_barrier
	s_setprio 1
	s_waitcnt lgkmcnt(0)
	v_mfma_f32_16x16x32_bf16 v[156:159], v[58:61], v[178:181], v[156:159]
	v_mfma_f32_16x16x32_bf16 v[152:155], v[66:69], v[178:181], v[152:155]
	v_mfma_f32_16x16x32_bf16 v[140:143], v[58:61], v[186:189], v[140:143]
	v_mfma_f32_16x16x32_bf16 v[136:139], v[66:69], v[186:189], v[136:139]
	v_mfma_f32_16x16x32_bf16 v[124:127], v[58:61], v[194:197], v[124:127]
	v_mfma_f32_16x16x32_bf16 v[120:123], v[66:69], v[194:197], v[120:123]
	v_mfma_f32_16x16x32_bf16 v[108:111], v[58:61], v[206:209], v[108:111]
	v_mfma_f32_16x16x32_bf16 v[104:107], v[66:69], v[206:209], v[104:107]
	v_mfma_f32_16x16x32_bf16 v[156:159], v[62:65], v[182:185], v[156:159]
	v_mfma_f32_16x16x32_bf16 v[152:155], v[70:73], v[182:185], v[152:155]
	v_mfma_f32_16x16x32_bf16 v[140:143], v[62:65], v[190:193], v[140:143]
	v_mfma_f32_16x16x32_bf16 v[136:139], v[70:73], v[190:193], v[136:139]
	v_mfma_f32_16x16x32_bf16 v[124:127], v[62:65], v[198:201], v[124:127]
	v_mfma_f32_16x16x32_bf16 v[120:123], v[70:73], v[198:201], v[120:123]
	v_mfma_f32_16x16x32_bf16 v[108:111], v[62:65], v[210:213], v[108:111]
	v_mfma_f32_16x16x32_bf16 v[104:107], v[70:73], v[210:213], v[104:107]
	v_mfma_f32_16x16x32_bf16 v[148:151], v[74:77], v[178:181], v[148:151]
	v_mfma_f32_16x16x32_bf16 v[144:147], v[82:85], v[178:181], v[144:147]
	v_mfma_f32_16x16x32_bf16 v[132:135], v[74:77], v[186:189], v[132:135]
	v_mfma_f32_16x16x32_bf16 v[128:131], v[82:85], v[186:189], v[128:131]
	v_mfma_f32_16x16x32_bf16 v[116:119], v[74:77], v[194:197], v[116:119]
	v_mfma_f32_16x16x32_bf16 v[112:115], v[82:85], v[194:197], v[112:115]
	v_mfma_f32_16x16x32_bf16 v[100:103], v[74:77], v[206:209], v[100:103]
	v_mfma_f32_16x16x32_bf16 v[96:99], v[82:85], v[206:209], v[96:99]
	v_mfma_f32_16x16x32_bf16 v[148:151], v[78:81], v[182:185], v[148:151]
	v_mfma_f32_16x16x32_bf16 v[144:147], v[172:175], v[182:185], v[144:147]
	v_mfma_f32_16x16x32_bf16 v[132:135], v[78:81], v[190:193], v[132:135]
	v_mfma_f32_16x16x32_bf16 v[128:131], v[172:175], v[190:193], v[128:131]
	v_mfma_f32_16x16x32_bf16 v[116:119], v[78:81], v[198:201], v[116:119]
	v_mfma_f32_16x16x32_bf16 v[112:115], v[172:175], v[198:201], v[112:115]
	v_mfma_f32_16x16x32_bf16 v[100:103], v[78:81], v[210:213], v[100:103]
	v_mfma_f32_16x16x32_bf16 v[96:99], v[172:175], v[210:213], v[96:99]
	s_setprio 0
	s_barrier
; #define PG8_STAGE(bufoff, gbase, voff) do { _Pragma("unroll") for (int _i = 0; _i < 2; ++_i) \
;         __builtin_amdgcn_global_load_lds((const unsigned*)((const char*)(gbase) + (voff)[_i]), (PG8_LAS unsigned*)(lds + (bufoff) + ldsw + _i * 8192), 16, 0, 0); } while (0)
; #define PG8_LDA(dst, b, h) do { _Pragma("unroll") for (int m = 0; m < 4; ++m) _Pragma("unroll") for (int k = 0; k < 2; ++k) dst[m][k] = *(const PG8_LAS bf16x8*)(lds + PG8_SA(b, h) + aoff + m * 2048 + k * 1024); } while (0)
; #define PG8_MMA(ai, bj, At, Bt) do { __builtin_amdgcn_s_setprio(1); _Pragma("unroll") for (int m = 0; m < 4; ++m) _Pragma("unroll") for (int n = 0; n < 2; ++n) _Pragma("unroll") for (int k = 0; k < 2; ++k) \
;         acc[ai][bj][m][n] = __builtin_amdgcn_mfma_f32_16x16x32_bf16(Bt[n][k], At[m][k], acc[ai][bj][m][n], 0, 0, 0); __builtin_amdgcn_s_setprio(0); } while (0)
; #define PG8_WAIT_V(n) asm volatile("s_waitcnt vmcnt(" #n ")" ::: "memory")
; #define PG8_WAIT_L(n) asm volatile("s_waitcnt lgkmcnt(" #n ")" ::: "memory")
; #define PG8_BAR __builtin_amdgcn_s_barrier()
; #define PG8_SCHED __builtin_amdgcn_sched_barrier(0)
; template <class Epi, class Sched, bool ALIGN_EPI = false, bool SP2 = false>
; __device__ __forceinline__ void gemm_phase(PG8_LAS unsigned char* lds, const Gemm g, const Sched& S, const Epi& E) {
;     ...
;             PG8_LDA(At, 1, 1); PG8_STAGE(PG8_SB(1, 0), b3, voffB); PG8_STAGE(PG8_SB(1, 1), b3 + hstep, voffB); PG8_STAGE(PG8_SA(1, 0), a3, voffA);
;             PG8_WAIT_V(8); PG8_WAIT_L(0); PG8_BAR; PG8_MMA(1, 0, At, B0); PG8_MMA(1, 1, At, B1); PG8_BAR; PG8_SCHED;
;     ...
;         if constexpr (ALIGN_EPI) { if (wr == 0) PG8_BAR; }
	s_add_i32 s8, s36, s2
	v_lshl_add_u64 v[90:91], v[214:215], 0, s[40:41]
	s_mov_b32 m0, s8
	ds_read_b128 v[178:181], v177 offset:49152
	ds_read_b128 v[182:185], v177 offset:50176
	ds_read_b128 v[186:189], v177 offset:51200
	ds_read_b128 v[190:193], v177 offset:52224
	ds_read_b128 v[194:197], v177 offset:53248
	ds_read_b128 v[198:201], v177 offset:54272
	ds_read_b128 v[206:209], v177 offset:55296
	ds_read_b128 v[210:213], v177 offset:56320
	global_load_lds_dwordx4 v[90:91], off
	s_add_i32 m0, s8, 0x2000
	s_add_u32 s6, s6, 0x40080
	v_lshl_add_u64 v[90:91], v[216:217], 0, s[40:41]
	s_addc_u32 s7, s7, 0
	s_add_i32 s8, s37, s2
	global_load_lds_dwordx4 v[90:91], off
	v_lshl_add_u64 v[90:91], s[6:7], 0, v[164:165]
	s_mov_b32 m0, s8
	s_nop 0
	global_load_lds_dwordx4 v[90:91], off
	v_lshl_add_u64 v[90:91], s[6:7], 0, v[160:161]
	s_add_i32 m0, s8, 0x2000
	s_nop 0
	global_load_lds_dwordx4 v[90:91], off
	v_lshl_add_u64 v[90:91], v[218:219], 0, s[40:41]
	s_mov_b32 m0, s16
	s_nop 0
	global_load_lds_dwordx4 v[90:91], off
	v_lshl_add_u64 v[90:91], v[220:221], 0, s[40:41]
	s_mov_b32 m0, s17
	s_nop 0
	global_load_lds_dwordx4 v[90:91], off
	s_waitcnt vmcnt(8)
	s_waitcnt lgkmcnt(0)
	s_barrier
	s_setprio 1
	s_waitcnt lgkmcnt(0)
	v_mfma_f32_16x16x32_bf16 v[90:93], v[58:61], v[178:181], v[92:95]
	v_mfma_f32_16x16x32_bf16 v[86:89], v[66:69], v[178:181], v[86:89]
	v_mfma_f32_16x16x32_bf16 v[46:49], v[58:61], v[186:189], v[46:49]
	v_mfma_f32_16x16x32_bf16 v[42:45], v[66:69], v[186:189], v[42:45]
	v_mfma_f32_16x16x32_bf16 v[30:33], v[58:61], v[194:197], v[30:33]
	v_mfma_f32_16x16x32_bf16 v[26:29], v[66:69], v[194:197], v[26:29]
	v_mfma_f32_16x16x32_bf16 v[14:17], v[58:61], v[206:209], v[14:17]
	v_mfma_f32_16x16x32_bf16 v[10:13], v[66:69], v[206:209], v[10:13]
	v_mfma_f32_16x16x32_bf16 v[92:95], v[62:65], v[182:185], v[90:93]
	v_mfma_f32_16x16x32_bf16 v[88:91], v[70:73], v[182:185], v[86:89]
	v_mfma_f32_16x16x32_bf16 v[46:49], v[62:65], v[190:193], v[46:49]
	v_mfma_f32_16x16x32_bf16 v[42:45], v[70:73], v[190:193], v[42:45]
	v_mfma_f32_16x16x32_bf16 v[30:33], v[62:65], v[198:201], v[30:33]
	v_mfma_f32_16x16x32_bf16 v[26:29], v[70:73], v[198:201], v[26:29]
	v_mfma_f32_16x16x32_bf16 v[14:17], v[62:65], v[210:213], v[14:17]
	v_mfma_f32_16x16x32_bf16 v[10:13], v[70:73], v[210:213], v[10:13]
	v_mfma_f32_16x16x32_bf16 v[54:57], v[74:77], v[178:181], v[54:57]
	v_mfma_f32_16x16x32_bf16 v[50:53], v[82:85], v[178:181], v[50:53]
	v_mfma_f32_16x16x32_bf16 v[38:41], v[74:77], v[186:189], v[38:41]
	v_mfma_f32_16x16x32_bf16 v[34:37], v[82:85], v[186:189], v[34:37]
	v_mfma_f32_16x16x32_bf16 v[22:25], v[74:77], v[194:197], v[22:25]
	v_mfma_f32_16x16x32_bf16 v[18:21], v[82:85], v[194:197], v[18:21]
	v_mfma_f32_16x16x32_bf16 v[6:9], v[74:77], v[206:209], v[6:9]
	v_mfma_f32_16x16x32_bf16 v[2:5], v[82:85], v[206:209], v[2:5]
	v_mfma_f32_16x16x32_bf16 v[54:57], v[78:81], v[182:185], v[54:57]
	v_mfma_f32_16x16x32_bf16 v[50:53], v[172:175], v[182:185], v[50:53]
	v_mfma_f32_16x16x32_bf16 v[38:41], v[78:81], v[190:193], v[38:41]
	v_mfma_f32_16x16x32_bf16 v[34:37], v[172:175], v[190:193], v[34:37]
	v_mfma_f32_16x16x32_bf16 v[22:25], v[78:81], v[198:201], v[22:25]
	v_mfma_f32_16x16x32_bf16 v[18:21], v[172:175], v[198:201], v[18:21]
	v_mfma_f32_16x16x32_bf16 v[6:9], v[78:81], v[210:213], v[6:9]
	v_mfma_f32_16x16x32_bf16 v[2:5], v[172:175], v[210:213], v[2:5]
	s_setprio 0
	s_barrier
	s_add_i32 s35, s35, 2
	s_add_u32 s4, s4, 0x100
	s_addc_u32 s5, s5, 0
	s_add_u32 s31, s31, 0x100
	s_addc_u32 s34, s34, 0
	s_cmp_gt_u32 s35, 13
	s_cbranch_scc0 .LBB0_739
	s_and_b64 vcc, exec, s[20:21]
	s_cbranch_vccz .LBB0_742
	s_barrier

; #define PG8_STAGE(bufoff, gbase, voff) do { _Pragma("unroll") for (int _i = 0; _i < 2; ++_i) \
;         __builtin_amdgcn_global_load_lds((const unsigned*)((const char*)(gbase) + (voff)[_i]), (PG8_LAS unsigned*)(lds + (bufoff) + ldsw + _i * 8192), 16, 0, 0); } while (0)
; #define PG8_LDA(dst, b, h) do { _Pragma("unroll") for (int m = 0; m < 4; ++m) _Pragma("unroll") for (int k = 0; k < 2; ++k) dst[m][k] = *(const PG8_LAS bf16x8*)(lds + PG8_SA(b, h) + aoff + m * 2048 + k * 1024); } while (0)
; #define PG8_LDB(dst, b, h) do { _Pragma("unroll") for (int n = 0; n < 2; ++n) _Pragma("unroll") for (int k = 0; k < 2; ++k) dst[n][k] = *(const PG8_LAS bf16x8*)(lds + PG8_SB(b, h) + boff + n * 2048 + k * 1024); } while (0)
; #define PG8_MMA(ai, bj, At, Bt) do { __builtin_amdgcn_s_setprio(1); _Pragma("unroll") for (int m = 0; m < 4; ++m) _Pragma("unroll") for (int n = 0; n < 2; ++n) _Pragma("unroll") for (int k = 0; k < 2; ++k) \
;         acc[ai][bj][m][n] = __builtin_amdgcn_mfma_f32_16x16x32_bf16(Bt[n][k], At[m][k], acc[ai][bj][m][n], 0, 0, 0); __builtin_amdgcn_s_setprio(0); } while (0)
; #define PG8_WAIT_V(n) asm volatile("s_waitcnt vmcnt(" #n ")" ::: "memory")
; #define PG8_WAIT_L(n) asm volatile("s_waitcnt lgkmcnt(" #n ")" ::: "memory")
; #define PG8_BAR __builtin_amdgcn_s_barrier()
; #define PG8_SCHED __builtin_amdgcn_sched_barrier(0)
; template <class Epi, class Sched, bool ALIGN_EPI = false, bool SP2 = false>
; __device__ __forceinline__ void gemm_phase(PG8_LAS unsigned char* lds, const Gemm g, const Sched& S, const Epi& E) {
;     ...
;         for (int t = 0; t < nt; t += 2) {
;             const bool last = (t == nt - 2);
;             const char* a1 = cA + (size_t)(t + 1) * kstep;
;             const char* a2 = last ? nA : cA + (size_t)(t + 2) * kstep; const char* b2 = last ? nB : cB + (size_t)(t + 2) * kstep;
;             const char* a3 = a2 + kstep; const char* b3 = b2 + kstep;
;             if (last && has_next) S.a_ready(nxt);
;             if constexpr (SP2) {
;             PG8_LDB(B0, 0, 0); PG8_LDB(B1, 0, 1); PG8_SCHED; PG8_LDA(At, 0, 0); PG8_STAGE(PG8_SA(1, 1), a1 + hstep, voffA);
;             PG8_WAIT_V(8); PG8_WAIT_L(0); PG8_BAR; PG8_MMA(0, 0, At, B0); PG8_MMA(0, 1, At, B1); PG8_BAR; PG8_SCHED;
;             PG8_LDA(At, 0, 1); PG8_STAGE(PG8_SB(0, 0), b2, voffB); PG8_STAGE(PG8_SB(0, 1), b2 + hstep, voffB); PG8_STAGE(PG8_SA(0, 0), a2, voffA);
.LBB0_891:
	s_add_i32 s10, s6, 2
	s_add_u32 s11, s4, 0x80
	s_addc_u32 s7, s5, 0
	s_cmp_eq_u32 s62, s6
	s_cselect_b32 s7, s55, s7
	s_cselect_b32 s6, s54, s11
	s_cselect_b32 s45, s57, s9
	s_cselect_b32 s44, s56, s8
	s_add_i32 s11, 0, 0x10000
	v_add_u32_e32 v0, s11, v204
	s_add_i32 s46, 0, 0x14000
	ds_read_b128 v[130:133], v0
	ds_read_b128 v[134:137], v0 offset:1024
	ds_read_b128 v[138:141], v0 offset:2048
	ds_read_b128 v[142:145], v0 offset:3072
	v_add_u32_e32 v0, s46, v204
	ds_read_b128 v[146:149], v0
	ds_read_b128 v[150:153], v0 offset:1024
	ds_read_b128 v[154:157], v0 offset:2048
	ds_read_b128 v[158:161], v0 offset:3072
	v_lshl_add_u64 v[206:207], s[4:5], 0, v[210:211]
	s_add_i32 m0, s16, 0xc000
	ds_read_b128 v[162:165], v247
	ds_read_b128 v[166:169], v247 offset:1024
	ds_read_b128 v[170:173], v247 offset:2048
	ds_read_b128 v[174:177], v247 offset:3072
	ds_read_b128 v[178:181], v247 offset:4096
	ds_read_b128 v[182:185], v247 offset:5120
	ds_read_b128 v[186:189], v247 offset:6144
	ds_read_b128 v[190:193], v247 offset:7168
	global_load_lds_dwordx4 v[206:207], off
	v_lshl_add_u64 v[206:207], s[4:5], 0, v[212:213]
	s_add_i32 m0, s16, 0xe000
	s_nop 0
	global_load_lds_dwordx4 v[206:207], off
	s_waitcnt vmcnt(8)
	s_waitcnt lgkmcnt(0)
	s_barrier
	s_setprio 1
	s_waitcnt lgkmcnt(0)
	v_mfma_f32_16x16x32_bf16 v[122:125], v[130:133], v[162:165], v[122:125]
	v_mfma_f32_16x16x32_bf16 v[126:129], v[138:141], v[162:165], v[126:129]
	v_mfma_f32_16x16x32_bf16 v[106:109], v[130:133], v[170:173], v[106:109]
	v_mfma_f32_16x16x32_bf16 v[110:113], v[138:141], v[170:173], v[110:113]
	v_mfma_f32_16x16x32_bf16 v[90:93], v[130:133], v[178:181], v[90:93]
	v_mfma_f32_16x16x32_bf16 v[94:97], v[138:141], v[178:181], v[94:97]
	v_mfma_f32_16x16x32_bf16 v[74:77], v[130:133], v[186:189], v[74:77]
	v_mfma_f32_16x16x32_bf16 v[78:81], v[138:141], v[186:189], v[78:81]
	v_mfma_f32_16x16x32_bf16 v[122:125], v[134:137], v[166:169], v[122:125]
	v_mfma_f32_16x16x32_bf16 v[126:129], v[142:145], v[166:169], v[126:129]
	v_mfma_f32_16x16x32_bf16 v[106:109], v[134:137], v[174:177], v[106:109]
	v_mfma_f32_16x16x32_bf16 v[110:113], v[142:145], v[174:177], v[110:113]
	v_mfma_f32_16x16x32_bf16 v[90:93], v[134:137], v[182:185], v[90:93]
	v_mfma_f32_16x16x32_bf16 v[94:97], v[142:145], v[182:185], v[94:97]
	v_mfma_f32_16x16x32_bf16 v[74:77], v[134:137], v[190:193], v[74:77]
	v_mfma_f32_16x16x32_bf16 v[78:81], v[142:145], v[190:193], v[78:81]
	v_mfma_f32_16x16x32_bf16 v[114:117], v[146:149], v[162:165], v[114:117]
	v_mfma_f32_16x16x32_bf16 v[118:121], v[154:157], v[162:165], v[118:121]
	v_mfma_f32_16x16x32_bf16 v[98:101], v[146:149], v[170:173], v[98:101]
	v_mfma_f32_16x16x32_bf16 v[102:105], v[154:157], v[170:173], v[102:105]
	v_mfma_f32_16x16x32_bf16 v[82:85], v[146:149], v[178:181], v[82:85]
	v_mfma_f32_16x16x32_bf16 v[86:89], v[154:157], v[178:181], v[86:89]
	v_mfma_f32_16x16x32_bf16 v[66:69], v[146:149], v[186:189], v[66:69]
	v_mfma_f32_16x16x32_bf16 v[70:73], v[154:157], v[186:189], v[70:73]
	v_mfma_f32_16x16x32_bf16 v[114:117], v[150:153], v[166:169], v[114:117]
	v_mfma_f32_16x16x32_bf16 v[118:121], v[158:161], v[166:169], v[118:121]
	v_mfma_f32_16x16x32_bf16 v[98:101], v[150:153], v[174:177], v[98:101]
	v_mfma_f32_16x16x32_bf16 v[102:105], v[158:161], v[174:177], v[102:105]
	v_mfma_f32_16x16x32_bf16 v[82:85], v[150:153], v[182:185], v[82:85]
	v_mfma_f32_16x16x32_bf16 v[86:89], v[158:161], v[182:185], v[86:89]
	v_mfma_f32_16x16x32_bf16 v[66:69], v[150:153], v[190:193], v[66:69]
	v_mfma_f32_16x16x32_bf16 v[70:73], v[158:161], v[190:193], v[70:73]
	s_setprio 0
	s_barrier
	s_add_i32 s11, s11, s15
	v_lshl_add_u64 v[206:207], s[44:45], 0, v[196:197]
	s_mov_b32 m0, s11
	ds_read_b128 v[162:165], v247 offset:16384
	ds_read_b128 v[166:169], v247 offset:17408
	ds_read_b128 v[170:173], v247 offset:18432
	ds_read_b128 v[174:177], v247 offset:19456
	ds_read_b128 v[178:181], v247 offset:20480
	ds_read_b128 v[182:185], v247 offset:21504
	ds_read_b128 v[186:189], v247 offset:22528
	ds_read_b128 v[190:193], v247 offset:23552
	global_load_lds_dwordx4 v[206:207], off
	s_add_i32 m0, s11, 0x2000
	v_lshl_add_u64 v[208:209], s[44:45], 0, v[200:201]
	s_add_u32 s44, s44, s2
	s_addc_u32 s45, s45, 0
	s_add_i32 s11, s46, s15
	global_load_lds_dwordx4 v[208:209], off
	v_lshl_add_u64 v[214:215], s[44:45], 0, v[196:197]
	s_mov_b32 m0, s11
	v_lshl_add_u64 v[216:217], s[44:45], 0, v[200:201]
	global_load_lds_dwordx4 v[214:215], off
	s_add_i32 m0, s11, 0x2000
	v_lshl_add_u64 v[218:219], s[6:7], 0, v[194:195]
	global_load_lds_dwordx4 v[216:217], off
	s_mov_b32 m0, s16
	v_lshl_add_u64 v[220:221], s[6:7], 0, v[198:199]
	global_load_lds_dwordx4 v[218:219], off
	s_mov_b32 m0, s17
	s_nop 0
	global_load_lds_dwordx4 v[220:221], off
	s_waitcnt vmcnt(8)
	s_waitcnt lgkmcnt(0)
	s_barrier
; #define PG8_STAGE(bufoff, gbase, voff) do { _Pragma("unroll") for (int _i = 0; _i < 2; ++_i) \
;         __builtin_amdgcn_global_load_lds((const unsigned*)((const char*)(gbase) + (voff)[_i]), (PG8_LAS unsigned*)(lds + (bufoff) + ldsw + _i * 8192), 16, 0, 0); } while (0)
; #define PG8_LDA(dst, b, h) do { _Pragma("unroll") for (int m = 0; m < 4; ++m) _Pragma("unroll") for (int k = 0; k < 2; ++k) dst[m][k] = *(const PG8_LAS bf16x8*)(lds + PG8_SA(b, h) + aoff + m * 2048 + k * 1024); } while (0)
; #define PG8_LDB(dst, b, h) do { _Pragma("unroll") for (int n = 0; n < 2; ++n) _Pragma("unroll") for (int k = 0; k < 2; ++k) dst[n][k] = *(const PG8_LAS bf16x8*)(lds + PG8_SB(b, h) + boff + n * 2048 + k * 1024); } while (0)
; #define PG8_MMA(ai, bj, At, Bt) do { __builtin_amdgcn_s_setprio(1); _Pragma("unroll") for (int m = 0; m < 4; ++m) _Pragma("unroll") for (int n = 0; n < 2; ++n) _Pragma("unroll") for (int k = 0; k < 2; ++k) \
;         acc[ai][bj][m][n] = __builtin_amdgcn_mfma_f32_16x16x32_bf16(Bt[n][k], At[m][k], acc[ai][bj][m][n], 0, 0, 0); __builtin_amdgcn_s_setprio(0); } while (0)
; #define PG8_WAIT_V(n) asm volatile("s_waitcnt vmcnt(" #n ")" ::: "memory")
; #define PG8_WAIT_L(n) asm volatile("s_waitcnt lgkmcnt(" #n ")" ::: "memory")
; #define PG8_BAR __builtin_amdgcn_s_barrier()
; #define PG8_SCHED __builtin_amdgcn_sched_barrier(0)
; template <class Epi, class Sched, bool ALIGN_EPI = false, bool SP2 = false>
; __device__ __forceinline__ void gemm_phase(PG8_LAS unsigned char* lds, const Gemm g, const Sched& S, const Epi& E) {
;     ...
;             PG8_WAIT_V(8); PG8_WAIT_L(0); PG8_BAR; PG8_MMA(1, 0, At, B0); PG8_MMA(1, 1, At, B1); PG8_BAR; PG8_SCHED;
;             PG8_LDB(B0, 1, 0); PG8_LDB(B1, 1, 1); PG8_SCHED; PG8_LDA(At, 1, 0); PG8_STAGE(PG8_SA(0, 1), a2 + hstep, voffA);
;             PG8_WAIT_V(8); PG8_WAIT_L(0); PG8_BAR; PG8_MMA(0, 0, At, B0); PG8_MMA(0, 1, At, B1); PG8_BAR; PG8_SCHED;
	s_setprio 1
	s_waitcnt lgkmcnt(0)
	v_mfma_f32_16x16x32_bf16 v[58:61], v[130:133], v[162:165], v[58:61]
	v_mfma_f32_16x16x32_bf16 v[62:65], v[138:141], v[162:165], v[62:65]
	v_mfma_f32_16x16x32_bf16 v[42:45], v[130:133], v[170:173], v[42:45]
	v_mfma_f32_16x16x32_bf16 v[46:49], v[138:141], v[170:173], v[46:49]
	v_mfma_f32_16x16x32_bf16 v[26:29], v[130:133], v[178:181], v[26:29]
	v_mfma_f32_16x16x32_bf16 v[30:33], v[138:141], v[178:181], v[30:33]
	v_mfma_f32_16x16x32_bf16 v[10:13], v[130:133], v[186:189], v[10:13]
	v_mfma_f32_16x16x32_bf16 v[14:17], v[138:141], v[186:189], v[14:17]
	v_mfma_f32_16x16x32_bf16 v[58:61], v[134:137], v[166:169], v[58:61]
	v_mfma_f32_16x16x32_bf16 v[62:65], v[142:145], v[166:169], v[62:65]
	v_mfma_f32_16x16x32_bf16 v[42:45], v[134:137], v[174:177], v[42:45]
	v_mfma_f32_16x16x32_bf16 v[46:49], v[142:145], v[174:177], v[46:49]
	v_mfma_f32_16x16x32_bf16 v[26:29], v[134:137], v[182:185], v[26:29]
	v_mfma_f32_16x16x32_bf16 v[30:33], v[142:145], v[182:185], v[30:33]
	v_mfma_f32_16x16x32_bf16 v[10:13], v[134:137], v[190:193], v[10:13]
	v_mfma_f32_16x16x32_bf16 v[14:17], v[142:145], v[190:193], v[14:17]
	v_mfma_f32_16x16x32_bf16 v[50:53], v[146:149], v[162:165], v[50:53]
	v_mfma_f32_16x16x32_bf16 v[54:57], v[154:157], v[162:165], v[54:57]
	v_mfma_f32_16x16x32_bf16 v[34:37], v[146:149], v[170:173], v[34:37]
	v_mfma_f32_16x16x32_bf16 v[38:41], v[154:157], v[170:173], v[38:41]
	v_mfma_f32_16x16x32_bf16 v[18:21], v[146:149], v[178:181], v[18:21]
	v_mfma_f32_16x16x32_bf16 v[22:25], v[154:157], v[178:181], v[22:25]
	v_mfma_f32_16x16x32_bf16 v[2:5], v[146:149], v[186:189], v[2:5]
	v_mfma_f32_16x16x32_bf16 v[6:9], v[154:157], v[186:189], v[6:9]
	v_mfma_f32_16x16x32_bf16 v[50:53], v[150:153], v[166:169], v[50:53]
	v_mfma_f32_16x16x32_bf16 v[54:57], v[158:161], v[166:169], v[54:57]
	v_mfma_f32_16x16x32_bf16 v[34:37], v[150:153], v[174:177], v[34:37]
	v_mfma_f32_16x16x32_bf16 v[38:41], v[158:161], v[174:177], v[38:41]
	v_mfma_f32_16x16x32_bf16 v[18:21], v[150:153], v[182:185], v[18:21]
	v_mfma_f32_16x16x32_bf16 v[22:25], v[158:161], v[182:185], v[22:25]
	v_mfma_f32_16x16x32_bf16 v[2:5], v[150:153], v[190:193], v[2:5]
	v_mfma_f32_16x16x32_bf16 v[6:9], v[158:161], v[190:193], v[6:9]
	s_setprio 0
	s_barrier
	s_add_i32 s11, 0, 0x18000
	v_add_u32_e32 v0, s11, v204
	s_add_i32 s44, 0, 0x1c000
	ds_read_b128 v[130:133], v0
	ds_read_b128 v[134:137], v0 offset:1024
	ds_read_b128 v[138:141], v0 offset:2048
	ds_read_b128 v[142:145], v0 offset:3072
	v_add_u32_e32 v0, s44, v204
	ds_read_b128 v[146:149], v0
	ds_read_b128 v[150:153], v0 offset:1024
	ds_read_b128 v[154:157], v0 offset:2048
	ds_read_b128 v[158:161], v0 offset:3072
	s_add_u32 s6, s6, s2
	s_addc_u32 s7, s7, 0
	s_mov_b32 m0, s18
	v_lshl_add_u64 v[222:223], s[6:7], 0, v[194:195]
	ds_read_b128 v[162:165], v247 offset:32768
	ds_read_b128 v[166:169], v247 offset:33792
	ds_read_b128 v[170:173], v247 offset:34816
	ds_read_b128 v[174:177], v247 offset:35840
	ds_read_b128 v[178:181], v247 offset:36864
	ds_read_b128 v[182:185], v247 offset:37888
	ds_read_b128 v[186:189], v247 offset:38912
	ds_read_b128 v[190:193], v247 offset:39936
	global_load_lds_dwordx4 v[222:223], off
	v_lshl_add_u64 v[222:223], s[6:7], 0, v[198:199]
	s_mov_b32 m0, s19
	s_nop 0
	global_load_lds_dwordx4 v[222:223], off
	s_waitcnt vmcnt(8)
	s_waitcnt lgkmcnt(0)
	s_barrier
	s_setprio 1
	s_waitcnt lgkmcnt(0)
	v_mfma_f32_16x16x32_bf16 v[122:125], v[130:133], v[162:165], v[122:125]
	v_mfma_f32_16x16x32_bf16 v[126:129], v[138:141], v[162:165], v[126:129]
	v_mfma_f32_16x16x32_bf16 v[106:109], v[130:133], v[170:173], v[106:109]
	v_mfma_f32_16x16x32_bf16 v[110:113], v[138:141], v[170:173], v[110:113]
	v_mfma_f32_16x16x32_bf16 v[90:93], v[130:133], v[178:181], v[90:93]
	v_mfma_f32_16x16x32_bf16 v[94:97], v[138:141], v[178:181], v[94:97]
	v_mfma_f32_16x16x32_bf16 v[74:77], v[130:133], v[186:189], v[74:77]
	v_mfma_f32_16x16x32_bf16 v[78:81], v[138:141], v[186:189], v[78:81]
	v_mfma_f32_16x16x32_bf16 v[122:125], v[134:137], v[166:169], v[122:125]
	v_mfma_f32_16x16x32_bf16 v[126:129], v[142:145], v[166:169], v[126:129]
	v_mfma_f32_16x16x32_bf16 v[106:109], v[134:137], v[174:177], v[106:109]
	v_mfma_f32_16x16x32_bf16 v[110:113], v[142:145], v[174:177], v[110:113]
	v_mfma_f32_16x16x32_bf16 v[90:93], v[134:137], v[182:185], v[90:93]
	v_mfma_f32_16x16x32_bf16 v[94:97], v[142:145], v[182:185], v[94:97]
	v_mfma_f32_16x16x32_bf16 v[74:77], v[134:137], v[190:193], v[74:77]
	v_mfma_f32_16x16x32_bf16 v[78:81], v[142:145], v[190:193], v[78:81]
	v_mfma_f32_16x16x32_bf16 v[114:117], v[146:149], v[162:165], v[114:117]
	v_mfma_f32_16x16x32_bf16 v[118:121], v[154:157], v[162:165], v[118:121]
	v_mfma_f32_16x16x32_bf16 v[98:101], v[146:149], v[170:173], v[98:101]
	v_mfma_f32_16x16x32_bf16 v[102:105], v[154:157], v[170:173], v[102:105]
	v_mfma_f32_16x16x32_bf16 v[82:85], v[146:149], v[178:181], v[82:85]
	v_mfma_f32_16x16x32_bf16 v[86:89], v[154:157], v[178:181], v[86:89]
	v_mfma_f32_16x16x32_bf16 v[66:69], v[146:149], v[186:189], v[66:69]
	v_mfma_f32_16x16x32_bf16 v[70:73], v[154:157], v[186:189], v[70:73]
	v_mfma_f32_16x16x32_bf16 v[114:117], v[150:153], v[166:169], v[114:117]
	v_mfma_f32_16x16x32_bf16 v[118:121], v[158:161], v[166:169], v[118:121]
	v_mfma_f32_16x16x32_bf16 v[98:101], v[150:153], v[174:177], v[98:101]
	v_mfma_f32_16x16x32_bf16 v[102:105], v[158:161], v[174:177], v[102:105]
	v_mfma_f32_16x16x32_bf16 v[82:85], v[150:153], v[182:185], v[82:85]
	v_mfma_f32_16x16x32_bf16 v[86:89], v[158:161], v[182:185], v[86:89]
	v_mfma_f32_16x16x32_bf16 v[66:69], v[150:153], v[190:193], v[66:69]
	v_mfma_f32_16x16x32_bf16 v[70:73], v[158:161], v[190:193], v[70:73]
	s_setprio 0
	s_barrier
; #define PG8_STAGE(bufoff, gbase, voff) do { _Pragma("unroll") for (int _i = 0; _i < 2; ++_i) \
;         __builtin_amdgcn_global_load_lds((const unsigned*)((const char*)(gbase) + (voff)[_i]), (PG8_LAS unsigned*)(lds + (bufoff) + ldsw + _i * 8192), 16, 0, 0); } while (0)
; #define PG8_LDA(dst, b, h) do { _Pragma("unroll") for (int m = 0; m < 4; ++m) _Pragma("unroll") for (int k = 0; k < 2; ++k) dst[m][k] = *(const PG8_LAS bf16x8*)(lds + PG8_SA(b, h) + aoff + m * 2048 + k * 1024); } while (0)
; #define PG8_MMA(ai, bj, At, Bt) do { __builtin_amdgcn_s_setprio(1); _Pragma("unroll") for (int m = 0; m < 4; ++m) _Pragma("unroll") for (int n = 0; n < 2; ++n) _Pragma("unroll") for (int k = 0; k < 2; ++k) \
;         acc[ai][bj][m][n] = __builtin_amdgcn_mfma_f32_16x16x32_bf16(Bt[n][k], At[m][k], acc[ai][bj][m][n], 0, 0, 0); __builtin_amdgcn_s_setprio(0); } while (0)
; #define PG8_WAIT_V(n) asm volatile("s_waitcnt vmcnt(" #n ")" ::: "memory")
; #define PG8_WAIT_L(n) asm volatile("s_waitcnt lgkmcnt(" #n ")" ::: "memory")
; #define PG8_BAR __builtin_amdgcn_s_barrier()
; #define PG8_SCHED __builtin_amdgcn_sched_barrier(0)
; template <class Epi, class Sched, bool ALIGN_EPI = false, bool SP2 = false>
; __device__ __forceinline__ void gemm_phase(PG8_LAS unsigned char* lds, const Gemm g, const Sched& S, const Epi& E) {
;     ...
;         for (int t = 0; t < nt; t += 2) {
;     ...
;             PG8_LDA(At, 1, 1); PG8_STAGE(PG8_SB(1, 0), b3, voffB); PG8_STAGE(PG8_SB(1, 1), b3 + hstep, voffB); PG8_STAGE(PG8_SA(1, 0), a3, voffA);
;             PG8_WAIT_V(8); PG8_WAIT_L(0); PG8_BAR; PG8_MMA(1, 0, At, B0); PG8_MMA(1, 1, At, B1); PG8_BAR; PG8_SCHED;
	s_add_i32 s6, s11, s15
	v_lshl_add_u64 v[206:207], v[206:207], 0, s[50:51]
	s_mov_b32 m0, s6
	ds_read_b128 v[162:165], v247 offset:49152
	ds_read_b128 v[166:169], v247 offset:50176
	ds_read_b128 v[170:173], v247 offset:51200
	ds_read_b128 v[174:177], v247 offset:52224
	ds_read_b128 v[178:181], v247 offset:53248
	ds_read_b128 v[182:185], v247 offset:54272
	ds_read_b128 v[186:189], v247 offset:55296
	ds_read_b128 v[190:193], v247 offset:56320
	global_load_lds_dwordx4 v[206:207], off
	v_lshl_add_u64 v[206:207], v[208:209], 0, s[50:51]
	s_add_i32 m0, s6, 0x2000
	s_add_i32 s6, s44, s15
	global_load_lds_dwordx4 v[206:207], off
	v_lshl_add_u64 v[206:207], v[214:215], 0, s[50:51]
	s_mov_b32 m0, s6
	s_nop 0
	global_load_lds_dwordx4 v[206:207], off
	v_lshl_add_u64 v[206:207], v[216:217], 0, s[50:51]
	s_add_i32 m0, s6, 0x2000
	s_nop 0
	global_load_lds_dwordx4 v[206:207], off
	v_lshl_add_u64 v[206:207], v[218:219], 0, s[50:51]
	s_mov_b32 m0, s31
	s_nop 0
	global_load_lds_dwordx4 v[206:207], off
	v_lshl_add_u64 v[206:207], v[220:221], 0, s[50:51]
	s_mov_b32 m0, s60
	s_nop 0
	global_load_lds_dwordx4 v[206:207], off
	s_waitcnt vmcnt(8)
	s_waitcnt lgkmcnt(0)
	s_barrier
	s_setprio 1
	s_waitcnt lgkmcnt(0)
	v_mfma_f32_16x16x32_bf16 v[58:61], v[130:133], v[162:165], v[58:61]
	v_mfma_f32_16x16x32_bf16 v[62:65], v[138:141], v[162:165], v[62:65]
	v_mfma_f32_16x16x32_bf16 v[42:45], v[130:133], v[170:173], v[42:45]
	v_mfma_f32_16x16x32_bf16 v[46:49], v[138:141], v[170:173], v[46:49]
	v_mfma_f32_16x16x32_bf16 v[26:29], v[130:133], v[178:181], v[26:29]
	v_mfma_f32_16x16x32_bf16 v[30:33], v[138:141], v[178:181], v[30:33]
	v_mfma_f32_16x16x32_bf16 v[10:13], v[130:133], v[186:189], v[10:13]
	v_mfma_f32_16x16x32_bf16 v[14:17], v[138:141], v[186:189], v[14:17]
	v_mfma_f32_16x16x32_bf16 v[58:61], v[134:137], v[166:169], v[58:61]
	v_mfma_f32_16x16x32_bf16 v[62:65], v[142:145], v[166:169], v[62:65]
	v_mfma_f32_16x16x32_bf16 v[42:45], v[134:137], v[174:177], v[42:45]
	v_mfma_f32_16x16x32_bf16 v[46:49], v[142:145], v[174:177], v[46:49]
	v_mfma_f32_16x16x32_bf16 v[26:29], v[134:137], v[182:185], v[26:29]
	v_mfma_f32_16x16x32_bf16 v[30:33], v[142:145], v[182:185], v[30:33]
	v_mfma_f32_16x16x32_bf16 v[10:13], v[134:137], v[190:193], v[10:13]
	v_mfma_f32_16x16x32_bf16 v[14:17], v[142:145], v[190:193], v[14:17]
	v_mfma_f32_16x16x32_bf16 v[50:53], v[146:149], v[162:165], v[50:53]
	v_mfma_f32_16x16x32_bf16 v[54:57], v[154:157], v[162:165], v[54:57]
	v_mfma_f32_16x16x32_bf16 v[34:37], v[146:149], v[170:173], v[34:37]
	v_mfma_f32_16x16x32_bf16 v[38:41], v[154:157], v[170:173], v[38:41]
	v_mfma_f32_16x16x32_bf16 v[18:21], v[146:149], v[178:181], v[18:21]
	v_mfma_f32_16x16x32_bf16 v[22:25], v[154:157], v[178:181], v[22:25]
	v_mfma_f32_16x16x32_bf16 v[2:5], v[146:149], v[186:189], v[2:5]
	v_mfma_f32_16x16x32_bf16 v[6:9], v[154:157], v[186:189], v[6:9]
	v_mfma_f32_16x16x32_bf16 v[50:53], v[150:153], v[166:169], v[50:53]
	v_mfma_f32_16x16x32_bf16 v[54:57], v[158:161], v[166:169], v[54:57]
	v_mfma_f32_16x16x32_bf16 v[34:37], v[150:153], v[174:177], v[34:37]
	v_mfma_f32_16x16x32_bf16 v[38:41], v[158:161], v[174:177], v[38:41]
	v_mfma_f32_16x16x32_bf16 v[18:21], v[150:153], v[182:185], v[18:21]
	v_mfma_f32_16x16x32_bf16 v[22:25], v[158:161], v[182:185], v[22:25]
	v_mfma_f32_16x16x32_bf16 v[2:5], v[150:153], v[190:193], v[2:5]
	v_mfma_f32_16x16x32_bf16 v[6:9], v[158:161], v[190:193], v[6:9]
	s_setprio 0
	s_barrier
	s_add_u32 s4, s4, 0x100
	s_addc_u32 s5, s5, 0
	s_add_u32 s8, s8, 0x100
	s_addc_u32 s9, s9, 0
	s_cmp_ge_u32 s10, s61
	s_mov_b32 s6, s10
	s_cbranch_scc0 .LBB0_891
	s_and_b64 vcc, exec, s[28:29]
	s_cbranch_vccz .LBB0_894
	s_barrier

; #define PG8_STAGE(bufoff, gbase, voff) do { _Pragma("unroll") for (int _i = 0; _i < 2; ++_i) \
;         __builtin_amdgcn_global_load_lds((const unsigned*)((const char*)(gbase) + (voff)[_i]), (PG8_LAS unsigned*)(lds + (bufoff) + ldsw + _i * 8192), 16, 0, 0); } while (0)
; #define PG8_LDA(dst, b, h) do { _Pragma("unroll") for (int m = 0; m < 4; ++m) _Pragma("unroll") for (int k = 0; k < 2; ++k) dst[m][k] = *(const PG8_LAS bf16x8*)(lds + PG8_SA(b, h) + aoff + m * 2048 + k * 1024); } while (0)
; #define PG8_LDB(dst, b, h) do { _Pragma("unroll") for (int n = 0; n < 2; ++n) _Pragma("unroll") for (int k = 0; k < 2; ++k) dst[n][k] = *(const PG8_LAS bf16x8*)(lds + PG8_SB(b, h) + boff + n * 2048 + k * 1024); } while (0)
; #define PG8_MMA(ai, bj, At, Bt) do { __builtin_amdgcn_s_setprio(1); _Pragma("unroll") for (int m = 0; m < 4; ++m) _Pragma("unroll") for (int n = 0; n < 2; ++n) _Pragma("unroll") for (int k = 0; k < 2; ++k) \
;         acc[ai][bj][m][n] = __builtin_amdgcn_mfma_f32_16x16x32_bf16(Bt[n][k], At[m][k], acc[ai][bj][m][n], 0, 0, 0); __builtin_amdgcn_s_setprio(0); } while (0)
; #define PG8_WAIT_V(n) asm volatile("s_waitcnt vmcnt(" #n ")" ::: "memory")
; #define PG8_WAIT_L(n) asm volatile("s_waitcnt lgkmcnt(" #n ")" ::: "memory")
; #define PG8_BAR __builtin_amdgcn_s_barrier()
; #define PG8_SCHED __builtin_amdgcn_sched_barrier(0)
; template <class Epi, class Sched, bool ALIGN_EPI = false, bool SP2 = false>
; __device__ __forceinline__ void gemm_phase(PG8_LAS unsigned char* lds, const Gemm g, const Sched& S, const Epi& E) {
;     ...
;         for (int t = 0; t < nt; t += 2) {
;             const bool last = (t == nt - 2);
;             const char* a1 = cA + (size_t)(t + 1) * kstep;
;             const char* a2 = last ? nA : cA + (size_t)(t + 2) * kstep; const char* b2 = last ? nB : cB + (size_t)(t + 2) * kstep;
;             const char* a3 = a2 + kstep; const char* b3 = b2 + kstep;
;             if (last && has_next) S.a_ready(nxt);
;             if constexpr (SP2) {
;             PG8_LDB(B0, 0, 0); PG8_LDB(B1, 0, 1); PG8_SCHED; PG8_LDA(At, 0, 0); PG8_STAGE(PG8_SA(1, 1), a1 + hstep, voffA);
;             PG8_WAIT_V(8); PG8_WAIT_L(0); PG8_BAR; PG8_MMA(0, 0, At, B0); PG8_MMA(0, 1, At, B1); PG8_BAR; PG8_SCHED;
;             PG8_LDA(At, 0, 1); PG8_STAGE(PG8_SB(0, 0), b2, voffB); PG8_STAGE(PG8_SB(0, 1), b2 + hstep, voffB); PG8_STAGE(PG8_SA(0, 0), a2, voffA);
.LBB0_1239:
	s_or_b32 s2, s7, 1
	s_lshl_b64 s[24:25], s[2:3], 7
	s_add_i32 s2, s7, 2
	s_lshl_b64 s[46:47], s[2:3], 7
	s_add_u32 s48, s16, s46
	s_addc_u32 s49, s17, s47
	s_and_b64 s[22:23], s[20:21], exec
	s_cselect_b32 s23, s40, s49
	s_cselect_b32 s22, s41, s48
	s_add_u32 s46, s14, s46
	s_addc_u32 s47, s15, s47
	s_and_b64 s[20:21], s[20:21], exec
	s_cselect_b32 s21, s42, s47
	s_cselect_b32 s20, s43, s46
	s_add_i32 s46, 0, 0x10000
	v_add_u32_e32 v139, s46, v0
	s_add_i32 s47, 0, 0x14000
	ds_read_b128 v[140:143], v139
	ds_read_b128 v[144:147], v139 offset:1024
	ds_read_b128 v[148:151], v139 offset:2048
	ds_read_b128 v[152:155], v139 offset:3072
	v_add_u32_e32 v139, s47, v0
	ds_read_b128 v[156:159], v139
	ds_read_b128 v[160:163], v139 offset:1024
	ds_read_b128 v[164:167], v139 offset:2048
	ds_read_b128 v[168:171], v139 offset:3072
	s_add_u32 s24, s44, s24
	s_addc_u32 s25, s45, s25
	v_lshl_add_u64 v[200:201], s[24:25], 0, v[130:131]
	s_add_i32 m0, s28, 0xc000
	ds_read_b128 v[172:175], v138
	ds_read_b128 v[176:179], v138 offset:1024
	ds_read_b128 v[180:183], v138 offset:2048
	ds_read_b128 v[184:187], v138 offset:3072
	ds_read_b128 v[188:191], v138 offset:4096
	ds_read_b128 v[192:195], v138 offset:5120
	ds_read_b128 v[196:199], v138 offset:6144
	ds_read_b128 v[206:209], v138 offset:7168
	global_load_lds_dwordx4 v[200:201], off
	v_lshl_add_u64 v[200:201], s[24:25], 0, v[134:135]
	s_add_i32 m0, s28, 0xe000
	s_nop 0
	global_load_lds_dwordx4 v[200:201], off
	s_waitcnt vmcnt(8)
	s_waitcnt lgkmcnt(0)
	s_barrier
	s_setprio 1
	s_waitcnt lgkmcnt(0)
	v_mfma_f32_16x16x32_bf16 v[126:129], v[140:143], v[172:175], v[126:129]
	v_mfma_f32_16x16x32_bf16 v[122:125], v[148:151], v[172:175], v[122:125]
	v_mfma_f32_16x16x32_bf16 v[118:121], v[140:143], v[180:183], v[118:121]
	v_mfma_f32_16x16x32_bf16 v[110:113], v[148:151], v[180:183], v[110:113]
	v_mfma_f32_16x16x32_bf16 v[102:105], v[140:143], v[188:191], v[102:105]
	v_mfma_f32_16x16x32_bf16 v[94:97], v[148:151], v[188:191], v[94:97]
	v_mfma_f32_16x16x32_bf16 v[86:89], v[140:143], v[196:199], v[86:89]
	v_mfma_f32_16x16x32_bf16 v[78:81], v[148:151], v[196:199], v[78:81]
	v_mfma_f32_16x16x32_bf16 v[126:129], v[144:147], v[176:179], v[126:129]
	v_mfma_f32_16x16x32_bf16 v[122:125], v[152:155], v[176:179], v[122:125]
	v_mfma_f32_16x16x32_bf16 v[118:121], v[144:147], v[184:187], v[118:121]
	v_mfma_f32_16x16x32_bf16 v[110:113], v[152:155], v[184:187], v[110:113]
	v_mfma_f32_16x16x32_bf16 v[102:105], v[144:147], v[192:195], v[102:105]
	v_mfma_f32_16x16x32_bf16 v[94:97], v[152:155], v[192:195], v[94:97]
	v_mfma_f32_16x16x32_bf16 v[86:89], v[144:147], v[206:209], v[86:89]
	v_mfma_f32_16x16x32_bf16 v[78:81], v[152:155], v[206:209], v[78:81]
	v_mfma_f32_16x16x32_bf16 v[114:117], v[156:159], v[172:175], v[114:117]
	v_mfma_f32_16x16x32_bf16 v[106:109], v[164:167], v[172:175], v[106:109]
	v_mfma_f32_16x16x32_bf16 v[98:101], v[156:159], v[180:183], v[98:101]
	v_mfma_f32_16x16x32_bf16 v[90:93], v[164:167], v[180:183], v[90:93]
	v_mfma_f32_16x16x32_bf16 v[82:85], v[156:159], v[188:191], v[82:85]
	v_mfma_f32_16x16x32_bf16 v[74:77], v[164:167], v[188:191], v[74:77]
	v_mfma_f32_16x16x32_bf16 v[70:73], v[156:159], v[196:199], v[70:73]
	v_mfma_f32_16x16x32_bf16 v[66:69], v[164:167], v[196:199], v[66:69]
	v_mfma_f32_16x16x32_bf16 v[114:117], v[160:163], v[176:179], v[114:117]
	v_mfma_f32_16x16x32_bf16 v[106:109], v[168:171], v[176:179], v[106:109]
	v_mfma_f32_16x16x32_bf16 v[98:101], v[160:163], v[184:187], v[98:101]
	v_mfma_f32_16x16x32_bf16 v[90:93], v[168:171], v[184:187], v[90:93]
	v_mfma_f32_16x16x32_bf16 v[82:85], v[160:163], v[192:195], v[82:85]
	v_mfma_f32_16x16x32_bf16 v[74:77], v[168:171], v[192:195], v[74:77]
	v_mfma_f32_16x16x32_bf16 v[70:73], v[160:163], v[206:209], v[70:73]
	v_mfma_f32_16x16x32_bf16 v[66:69], v[168:171], v[206:209], v[66:69]
	s_setprio 0
	s_barrier
	s_add_i32 s24, s46, s27
	v_lshl_add_u64 v[200:201], s[20:21], 0, v[132:133]
	s_mov_b32 m0, s24
	ds_read_b128 v[172:175], v138 offset:16384
	ds_read_b128 v[176:179], v138 offset:17408
	ds_read_b128 v[180:183], v138 offset:18432
	ds_read_b128 v[184:187], v138 offset:19456
	ds_read_b128 v[188:191], v138 offset:20480
	ds_read_b128 v[192:195], v138 offset:21504
	ds_read_b128 v[196:199], v138 offset:22528
	ds_read_b128 v[206:209], v138 offset:23552
	global_load_lds_dwordx4 v[200:201], off
	s_add_i32 m0, s24, 0x2000
	s_add_u32 s24, s20, 0x40000
	v_lshl_add_u64 v[210:211], s[20:21], 0, v[136:137]
	s_addc_u32 s25, s21, 0
	s_add_i32 s46, s47, s27
	global_load_lds_dwordx4 v[210:211], off
	v_lshl_add_u64 v[212:213], s[24:25], 0, v[132:133]
	s_mov_b32 m0, s46
	v_lshl_add_u64 v[214:215], s[22:23], 0, v[134:135]
	global_load_lds_dwordx4 v[212:213], off
	v_lshl_add_u64 v[212:213], s[24:25], 0, v[136:137]
	s_add_i32 m0, s46, 0x2000
	s_nop 0
	global_load_lds_dwordx4 v[212:213], off
	v_lshl_add_u64 v[212:213], s[22:23], 0, v[130:131]
	s_mov_b32 m0, s28
	s_nop 0
	global_load_lds_dwordx4 v[212:213], off
	s_mov_b32 m0, s29
	s_nop 0
	global_load_lds_dwordx4 v[214:215], off
	s_waitcnt vmcnt(8)
	s_waitcnt lgkmcnt(0)
	s_barrier
; #define PG8_STAGE(bufoff, gbase, voff) do { _Pragma("unroll") for (int _i = 0; _i < 2; ++_i) \
;         __builtin_amdgcn_global_load_lds((const unsigned*)((const char*)(gbase) + (voff)[_i]), (PG8_LAS unsigned*)(lds + (bufoff) + ldsw + _i * 8192), 16, 0, 0); } while (0)
; #define PG8_LDA(dst, b, h) do { _Pragma("unroll") for (int m = 0; m < 4; ++m) _Pragma("unroll") for (int k = 0; k < 2; ++k) dst[m][k] = *(const PG8_LAS bf16x8*)(lds + PG8_SA(b, h) + aoff + m * 2048 + k * 1024); } while (0)
; #define PG8_LDB(dst, b, h) do { _Pragma("unroll") for (int n = 0; n < 2; ++n) _Pragma("unroll") for (int k = 0; k < 2; ++k) dst[n][k] = *(const PG8_LAS bf16x8*)(lds + PG8_SB(b, h) + boff + n * 2048 + k * 1024); } while (0)
; #define PG8_MMA(ai, bj, At, Bt) do { __builtin_amdgcn_s_setprio(1); _Pragma("unroll") for (int m = 0; m < 4; ++m) _Pragma("unroll") for (int n = 0; n < 2; ++n) _Pragma("unroll") for (int k = 0; k < 2; ++k) \
;         acc[ai][bj][m][n] = __builtin_amdgcn_mfma_f32_16x16x32_bf16(Bt[n][k], At[m][k], acc[ai][bj][m][n], 0, 0, 0); __builtin_amdgcn_s_setprio(0); } while (0)
; #define PG8_WAIT_V(n) asm volatile("s_waitcnt vmcnt(" #n ")" ::: "memory")
; #define PG8_WAIT_L(n) asm volatile("s_waitcnt lgkmcnt(" #n ")" ::: "memory")
; #define PG8_BAR __builtin_amdgcn_s_barrier()
; #define PG8_SCHED __builtin_amdgcn_sched_barrier(0)
; template <class Epi, class Sched, bool ALIGN_EPI = false, bool SP2 = false>
; __device__ __forceinline__ void gemm_phase(PG8_LAS unsigned char* lds, const Gemm g, const Sched& S, const Epi& E) {
;     ...
;             PG8_WAIT_V(8); PG8_WAIT_L(0); PG8_BAR; PG8_MMA(1, 0, At, B0); PG8_MMA(1, 1, At, B1); PG8_BAR; PG8_SCHED;
;             PG8_LDB(B0, 1, 0); PG8_LDB(B1, 1, 1); PG8_SCHED; PG8_LDA(At, 1, 0); PG8_STAGE(PG8_SA(0, 1), a2 + hstep, voffA);
;             PG8_WAIT_V(8); PG8_WAIT_L(0); PG8_BAR; PG8_MMA(0, 0, At, B0); PG8_MMA(0, 1, At, B1); PG8_BAR; PG8_SCHED;
	s_setprio 1
	s_waitcnt lgkmcnt(0)
	v_mfma_f32_16x16x32_bf16 v[62:65], v[140:143], v[172:175], v[62:65]
	v_mfma_f32_16x16x32_bf16 v[58:61], v[148:151], v[172:175], v[58:61]
	v_mfma_f32_16x16x32_bf16 v[54:57], v[140:143], v[180:183], v[54:57]
	v_mfma_f32_16x16x32_bf16 v[46:49], v[148:151], v[180:183], v[46:49]
	v_mfma_f32_16x16x32_bf16 v[38:41], v[140:143], v[188:191], v[38:41]
	v_mfma_f32_16x16x32_bf16 v[30:33], v[148:151], v[188:191], v[30:33]
	v_mfma_f32_16x16x32_bf16 v[22:25], v[140:143], v[196:199], v[22:25]
	v_mfma_f32_16x16x32_bf16 v[14:17], v[148:151], v[196:199], v[14:17]
	v_mfma_f32_16x16x32_bf16 v[62:65], v[144:147], v[176:179], v[62:65]
	v_mfma_f32_16x16x32_bf16 v[58:61], v[152:155], v[176:179], v[58:61]
	v_mfma_f32_16x16x32_bf16 v[54:57], v[144:147], v[184:187], v[54:57]
	v_mfma_f32_16x16x32_bf16 v[46:49], v[152:155], v[184:187], v[46:49]
	v_mfma_f32_16x16x32_bf16 v[38:41], v[144:147], v[192:195], v[38:41]
	v_mfma_f32_16x16x32_bf16 v[30:33], v[152:155], v[192:195], v[30:33]
	v_mfma_f32_16x16x32_bf16 v[22:25], v[144:147], v[206:209], v[22:25]
	v_mfma_f32_16x16x32_bf16 v[14:17], v[152:155], v[206:209], v[14:17]
	v_mfma_f32_16x16x32_bf16 v[50:53], v[156:159], v[172:175], v[50:53]
	v_mfma_f32_16x16x32_bf16 v[42:45], v[164:167], v[172:175], v[42:45]
	v_mfma_f32_16x16x32_bf16 v[34:37], v[156:159], v[180:183], v[34:37]
	v_mfma_f32_16x16x32_bf16 v[26:29], v[164:167], v[180:183], v[26:29]
	v_mfma_f32_16x16x32_bf16 v[18:21], v[156:159], v[188:191], v[18:21]
	v_mfma_f32_16x16x32_bf16 v[10:13], v[164:167], v[188:191], v[10:13]
	v_mfma_f32_16x16x32_bf16 v[6:9], v[156:159], v[196:199], v[6:9]
	v_mfma_f32_16x16x32_bf16 v[2:5], v[164:167], v[196:199], v[2:5]
	v_mfma_f32_16x16x32_bf16 v[50:53], v[160:163], v[176:179], v[50:53]
	v_mfma_f32_16x16x32_bf16 v[42:45], v[168:171], v[176:179], v[42:45]
	v_mfma_f32_16x16x32_bf16 v[34:37], v[160:163], v[184:187], v[34:37]
	v_mfma_f32_16x16x32_bf16 v[26:29], v[168:171], v[184:187], v[26:29]
	v_mfma_f32_16x16x32_bf16 v[18:21], v[160:163], v[192:195], v[18:21]
	v_mfma_f32_16x16x32_bf16 v[10:13], v[168:171], v[192:195], v[10:13]
	v_mfma_f32_16x16x32_bf16 v[6:9], v[160:163], v[206:209], v[6:9]
	v_mfma_f32_16x16x32_bf16 v[2:5], v[168:171], v[206:209], v[2:5]
	s_setprio 0
	s_barrier
	s_add_i32 s24, 0, 0x18000
	v_add_u32_e32 v139, s24, v0
	s_add_i32 s25, 0, 0x1c000
	ds_read_b128 v[140:143], v139
	ds_read_b128 v[144:147], v139 offset:1024
	ds_read_b128 v[148:151], v139 offset:2048
	ds_read_b128 v[152:155], v139 offset:3072
	v_add_u32_e32 v139, s25, v0
	ds_read_b128 v[156:159], v139
	ds_read_b128 v[160:163], v139 offset:1024
	ds_read_b128 v[164:167], v139 offset:2048
	ds_read_b128 v[168:171], v139 offset:3072
	s_add_u32 s22, s22, 0x40000
	s_addc_u32 s23, s23, 0
	s_mov_b32 m0, s31
	v_lshl_add_u64 v[216:217], s[22:23], 0, v[130:131]
	ds_read_b128 v[172:175], v138 offset:32768
	ds_read_b128 v[176:179], v138 offset:33792
	ds_read_b128 v[180:183], v138 offset:34816
	ds_read_b128 v[184:187], v138 offset:35840
	ds_read_b128 v[188:191], v138 offset:36864
	ds_read_b128 v[192:195], v138 offset:37888
	ds_read_b128 v[196:199], v138 offset:38912
	ds_read_b128 v[206:209], v138 offset:39936
	global_load_lds_dwordx4 v[216:217], off
	v_lshl_add_u64 v[216:217], s[22:23], 0, v[134:135]
	s_mov_b32 m0, s34
	s_nop 0
	global_load_lds_dwordx4 v[216:217], off
	s_waitcnt vmcnt(8)
	s_waitcnt lgkmcnt(0)
	s_barrier
	s_setprio 1
	s_waitcnt lgkmcnt(0)
	v_mfma_f32_16x16x32_bf16 v[126:129], v[140:143], v[172:175], v[126:129]
	v_mfma_f32_16x16x32_bf16 v[122:125], v[148:151], v[172:175], v[122:125]
	v_mfma_f32_16x16x32_bf16 v[118:121], v[140:143], v[180:183], v[118:121]
	v_mfma_f32_16x16x32_bf16 v[110:113], v[148:151], v[180:183], v[110:113]
	v_mfma_f32_16x16x32_bf16 v[102:105], v[140:143], v[188:191], v[102:105]
	v_mfma_f32_16x16x32_bf16 v[94:97], v[148:151], v[188:191], v[94:97]
	v_mfma_f32_16x16x32_bf16 v[86:89], v[140:143], v[196:199], v[86:89]
	v_mfma_f32_16x16x32_bf16 v[78:81], v[148:151], v[196:199], v[78:81]
	v_mfma_f32_16x16x32_bf16 v[126:129], v[144:147], v[176:179], v[126:129]
	v_mfma_f32_16x16x32_bf16 v[122:125], v[152:155], v[176:179], v[122:125]
	v_mfma_f32_16x16x32_bf16 v[118:121], v[144:147], v[184:187], v[118:121]
	v_mfma_f32_16x16x32_bf16 v[110:113], v[152:155], v[184:187], v[110:113]
	v_mfma_f32_16x16x32_bf16 v[102:105], v[144:147], v[192:195], v[102:105]
	v_mfma_f32_16x16x32_bf16 v[94:97], v[152:155], v[192:195], v[94:97]
	v_mfma_f32_16x16x32_bf16 v[86:89], v[144:147], v[206:209], v[86:89]
	v_mfma_f32_16x16x32_bf16 v[78:81], v[152:155], v[206:209], v[78:81]
	v_mfma_f32_16x16x32_bf16 v[114:117], v[156:159], v[172:175], v[114:117]
	v_mfma_f32_16x16x32_bf16 v[106:109], v[164:167], v[172:175], v[106:109]
	v_mfma_f32_16x16x32_bf16 v[98:101], v[156:159], v[180:183], v[98:101]
	v_mfma_f32_16x16x32_bf16 v[90:93], v[164:167], v[180:183], v[90:93]
	v_mfma_f32_16x16x32_bf16 v[82:85], v[156:159], v[188:191], v[82:85]
	v_mfma_f32_16x16x32_bf16 v[74:77], v[164:167], v[188:191], v[74:77]
	v_mfma_f32_16x16x32_bf16 v[70:73], v[156:159], v[196:199], v[70:73]
	v_mfma_f32_16x16x32_bf16 v[66:69], v[164:167], v[196:199], v[66:69]
	v_mfma_f32_16x16x32_bf16 v[114:117], v[160:163], v[176:179], v[114:117]
	v_mfma_f32_16x16x32_bf16 v[106:109], v[168:171], v[176:179], v[106:109]
	v_mfma_f32_16x16x32_bf16 v[98:101], v[160:163], v[184:187], v[98:101]
	v_mfma_f32_16x16x32_bf16 v[90:93], v[168:171], v[184:187], v[90:93]
	v_mfma_f32_16x16x32_bf16 v[82:85], v[160:163], v[192:195], v[82:85]
	v_mfma_f32_16x16x32_bf16 v[74:77], v[168:171], v[192:195], v[74:77]
	v_mfma_f32_16x16x32_bf16 v[70:73], v[160:163], v[206:209], v[70:73]
	v_mfma_f32_16x16x32_bf16 v[66:69], v[168:171], v[206:209], v[66:69]
	s_setprio 0
	s_barrier
; #define PG8_STAGE(bufoff, gbase, voff) do { _Pragma("unroll") for (int _i = 0; _i < 2; ++_i) \
;         __builtin_amdgcn_global_load_lds((const unsigned*)((const char*)(gbase) + (voff)[_i]), (PG8_LAS unsigned*)(lds + (bufoff) + ldsw + _i * 8192), 16, 0, 0); } while (0)
; #define PG8_LDA(dst, b, h) do { _Pragma("unroll") for (int m = 0; m < 4; ++m) _Pragma("unroll") for (int k = 0; k < 2; ++k) dst[m][k] = *(const PG8_LAS bf16x8*)(lds + PG8_SA(b, h) + aoff + m * 2048 + k * 1024); } while (0)
; #define PG8_MMA(ai, bj, At, Bt) do { __builtin_amdgcn_s_setprio(1); _Pragma("unroll") for (int m = 0; m < 4; ++m) _Pragma("unroll") for (int n = 0; n < 2; ++n) _Pragma("unroll") for (int k = 0; k < 2; ++k) \
;         acc[ai][bj][m][n] = __builtin_amdgcn_mfma_f32_16x16x32_bf16(Bt[n][k], At[m][k], acc[ai][bj][m][n], 0, 0, 0); __builtin_amdgcn_s_setprio(0); } while (0)
; #define PG8_WAIT_V(n) asm volatile("s_waitcnt vmcnt(" #n ")" ::: "memory")
; #define PG8_WAIT_L(n) asm volatile("s_waitcnt lgkmcnt(" #n ")" ::: "memory")
; #define PG8_BAR __builtin_amdgcn_s_barrier()
; #define PG8_SCHED __builtin_amdgcn_sched_barrier(0)
; template <class Epi, class Sched, bool ALIGN_EPI = false, bool SP2 = false>
; __device__ __forceinline__ void gemm_phase(PG8_LAS unsigned char* lds, const Gemm g, const Sched& S, const Epi& E) {
;     ...
;         for (int t = 0; t < nt; t += 2) {
;     ...
;             PG8_LDA(At, 1, 1); PG8_STAGE(PG8_SB(1, 0), b3, voffB); PG8_STAGE(PG8_SB(1, 1), b3 + hstep, voffB); PG8_STAGE(PG8_SA(1, 0), a3, voffA);
;             PG8_WAIT_V(8); PG8_WAIT_L(0); PG8_BAR; PG8_MMA(1, 0, At, B0); PG8_MMA(1, 1, At, B1); PG8_BAR; PG8_SCHED;
	s_mov_b64 s[46:47], 0x80
	s_add_i32 s22, s24, s27
	v_lshl_add_u64 v[200:201], v[200:201], 0, s[46:47]
	s_mov_b32 m0, s22
	ds_read_b128 v[172:175], v138 offset:49152
	ds_read_b128 v[176:179], v138 offset:50176
	ds_read_b128 v[180:183], v138 offset:51200
	ds_read_b128 v[184:187], v138 offset:52224
	ds_read_b128 v[188:191], v138 offset:53248
	ds_read_b128 v[192:195], v138 offset:54272
	ds_read_b128 v[196:199], v138 offset:55296
	ds_read_b128 v[206:209], v138 offset:56320
	global_load_lds_dwordx4 v[200:201], off
	s_add_i32 m0, s22, 0x2000
	s_add_u32 s20, s20, 0x40080
	v_lshl_add_u64 v[200:201], v[210:211], 0, s[46:47]
	s_addc_u32 s21, s21, 0
	s_add_i32 s22, s25, s27
	global_load_lds_dwordx4 v[200:201], off
	v_lshl_add_u64 v[200:201], s[20:21], 0, v[132:133]
	s_mov_b32 m0, s22
	s_nop 0
	global_load_lds_dwordx4 v[200:201], off
	v_lshl_add_u64 v[200:201], s[20:21], 0, v[136:137]
	s_add_i32 m0, s22, 0x2000
	s_nop 0
	global_load_lds_dwordx4 v[200:201], off
	v_lshl_add_u64 v[200:201], v[212:213], 0, s[46:47]
	s_mov_b32 m0, s35
	s_nop 0
	global_load_lds_dwordx4 v[200:201], off
	v_lshl_add_u64 v[200:201], v[214:215], 0, s[46:47]
	s_mov_b32 m0, s36
	s_nop 0
	global_load_lds_dwordx4 v[200:201], off
	s_waitcnt vmcnt(8)
	s_waitcnt lgkmcnt(0)
	s_barrier
	s_setprio 1
	s_waitcnt lgkmcnt(0)
	v_mfma_f32_16x16x32_bf16 v[62:65], v[140:143], v[172:175], v[62:65]
	v_mfma_f32_16x16x32_bf16 v[58:61], v[148:151], v[172:175], v[58:61]
	v_mfma_f32_16x16x32_bf16 v[54:57], v[140:143], v[180:183], v[54:57]
	v_mfma_f32_16x16x32_bf16 v[46:49], v[148:151], v[180:183], v[46:49]
	v_mfma_f32_16x16x32_bf16 v[38:41], v[140:143], v[188:191], v[38:41]
	v_mfma_f32_16x16x32_bf16 v[30:33], v[148:151], v[188:191], v[30:33]
	v_mfma_f32_16x16x32_bf16 v[22:25], v[140:143], v[196:199], v[22:25]
	v_mfma_f32_16x16x32_bf16 v[14:17], v[148:151], v[196:199], v[14:17]
	v_mfma_f32_16x16x32_bf16 v[62:65], v[144:147], v[176:179], v[62:65]
	v_mfma_f32_16x16x32_bf16 v[58:61], v[152:155], v[176:179], v[58:61]
	v_mfma_f32_16x16x32_bf16 v[54:57], v[144:147], v[184:187], v[54:57]
	v_mfma_f32_16x16x32_bf16 v[46:49], v[152:155], v[184:187], v[46:49]
	v_mfma_f32_16x16x32_bf16 v[38:41], v[144:147], v[192:195], v[38:41]
	v_mfma_f32_16x16x32_bf16 v[30:33], v[152:155], v[192:195], v[30:33]
	v_mfma_f32_16x16x32_bf16 v[22:25], v[144:147], v[206:209], v[22:25]
	v_mfma_f32_16x16x32_bf16 v[14:17], v[152:155], v[206:209], v[14:17]
	v_mfma_f32_16x16x32_bf16 v[50:53], v[156:159], v[172:175], v[50:53]
	v_mfma_f32_16x16x32_bf16 v[42:45], v[164:167], v[172:175], v[42:45]
	v_mfma_f32_16x16x32_bf16 v[34:37], v[156:159], v[180:183], v[34:37]
	v_mfma_f32_16x16x32_bf16 v[26:29], v[164:167], v[180:183], v[26:29]
	v_mfma_f32_16x16x32_bf16 v[18:21], v[156:159], v[188:191], v[18:21]
	v_mfma_f32_16x16x32_bf16 v[10:13], v[164:167], v[188:191], v[10:13]
	v_mfma_f32_16x16x32_bf16 v[6:9], v[156:159], v[196:199], v[6:9]
	v_mfma_f32_16x16x32_bf16 v[2:5], v[164:167], v[196:199], v[2:5]
	v_mfma_f32_16x16x32_bf16 v[50:53], v[160:163], v[176:179], v[50:53]
	v_mfma_f32_16x16x32_bf16 v[42:45], v[168:171], v[176:179], v[42:45]
	v_mfma_f32_16x16x32_bf16 v[34:37], v[160:163], v[184:187], v[34:37]
	v_mfma_f32_16x16x32_bf16 v[26:29], v[168:171], v[184:187], v[26:29]
	v_mfma_f32_16x16x32_bf16 v[18:21], v[160:163], v[192:195], v[18:21]
	v_mfma_f32_16x16x32_bf16 v[10:13], v[168:171], v[192:195], v[10:13]
	v_mfma_f32_16x16x32_bf16 v[6:9], v[160:163], v[206:209], v[6:9]
	v_mfma_f32_16x16x32_bf16 v[2:5], v[168:171], v[206:209], v[2:5]
	s_setprio 0
	s_barrier
	s_cmp_gt_u32 s7, 13
	s_mov_b32 s7, s2
	s_cbranch_scc1 .LBB0_1250
